# RWKV epilogue (GroupNorm+bonus+gate) moved to waves 4-7, running one 8-token block behind the MFMA recurrence (per-block s_barrier sync); compiler epilogue removed
# speedup vs baseline: 1.2851x; 1.0094x over previous
.LBB0_586:
.Lrw_entry:
	v_readfirstlane_b32 s0, v180
	s_nop 1
	s_cmpk_ge_u32 s0, 0x100
	s_cbranch_scc1 .Lrw_epi
	v_and_b32_e32 v222, 15, v180
	v_bfe_u32 v223, v180, 4, 2
	v_lshrrev_b32_e32 v240, 6, v180
	v_and_b32_e32 v176, 7, v222
	v_mul_u32_u24_e32 v176, 0x110, v176
	v_and_b32_e32 v177, 8, v222
	v_mul_u32_u24_e32 v177, 0x880, v177
	v_lshl_add_u32 v168, v223, 4, v176
	v_add_u32_e32 v168, v168, v177
	v_lshlrev_b32_e32 v178, 6, v240
	v_lshl_add_u32 v178, v222, 2, v178
	v_lshl_add_u32 v169, v223, 8, v178
	v_add_u32_e32 v169, s41, v169
	v_lshl_add_u32 v175, v223, 10, v178
	v_add_u32_e32 v175, 0x1f000, v175
	v_mov_b32_e32 v170, 0x15800
	v_lshlrev_b32_e32 v176, 5, v222
	v_lshl_add_u32 v176, v223, 2, v176
	v_and_b32_e32 v177, 8, v222
	v_lshl_add_u32 v172, v177, 5, v176
	v_add_u32_e32 v171, 0x15900, v172
	v_add_u32_e32 v172, 0x15800, v172
	v_mul_u32_u24_e32 v176, 0x110, v223
	v_lshl_add_u32 v173, v222, 2, v176
	v_add_u32_e32 v173, 0x8800, v173
	v_add_u32_e32 v2, 0x440, v173
	v_add_u32_e32 v3, 0x4400, v173
	v_add_u32_e32 v5, 0x4840, v173
	v_lshlrev_b32_e32 v174, 4, v223
	v_add_u32_e32 v174, 0x11000, v174
	v_cmp_eq_u32_e32 vcc, 1, v223
	v_cmp_eq_u32_e64 s[4:5], 2, v223
	v_cmp_eq_u32_e64 s[6:7], 3, v223
	s_mov_b32 s8, 0
	s_mov_b32 s9, -1
	v_mov_b32_e32 v198, 1.0
	v_mov_b32_e32 v199, 1.0
	v_mov_b32_e32 v200, 1.0
	v_mov_b32_e32 v201, 1.0
	v_mov_b32_e32 v202, 1.0
	v_mov_b32_e32 v203, 1.0
	v_mov_b32_e32 v204, 1.0
	v_mov_b32_e32 v205, 1.0
	v_mov_b32_e32 v206, 1.0
	v_mov_b32_e32 v207, 1.0
	v_mov_b32_e32 v208, 1.0
	v_mov_b32_e32 v209, 1.0
	v_mov_b32_e32 v210, 1.0
	v_mov_b32_e32 v211, 1.0
	v_mov_b32_e32 v212, 1.0
	v_mov_b32_e32 v213, 1.0
	ds_read_b128 v[44:47], v168 offset:0
	ds_read_b128 v[48:51], v168 offset:64
	ds_read_b128 v[68:71], v168 offset:128
	ds_read_b128 v[96:99], v168 offset:192
	ds_read_b32 v216, v171 offset:0
	ds_read_b32 v217, v171 offset:16
	ds_read_b32 v214, v169 offset:0
	ds_read_b32 v215, v169 offset:1024
	ds_read_b128 v[124:127], v170 offset:32
	ds_read_b128 v[128:131], v170 offset:64
	ds_read_b128 v[132:135], v170 offset:96
	ds_read_b128 v[136:139], v170 offset:128
	ds_read_b128 v[144:147], v170 offset:160
	ds_read_b128 v[148:151], v170 offset:176
	ds_read_b128 v[152:155], v170 offset:192
	ds_read_b128 v[156:159], v170 offset:208
	ds_read_b128 v[160:163], v170 offset:224
	ds_read_b128 v[164:167], v170 offset:240
	ds_read_b32 v218, v172 offset:0
	ds_read_b32 v219, v172 offset:16
	ds_read2_b32 v[182:183], v173 offset0:0 offset1:16
	ds_read2_b32 v[184:185], v173 offset0:32 offset1:48
	ds_read2_b32 v[186:187], v2 offset0:0 offset1:16
	ds_read2_b32 v[188:189], v2 offset0:32 offset1:48
	ds_read2_b32 v[190:191], v3 offset0:0 offset1:16
	ds_read2_b32 v[192:193], v3 offset0:32 offset1:48
	ds_read2_b32 v[194:195], v5 offset0:0 offset1:16
	ds_read2_b32 v[196:197], v5 offset0:32 offset1:48
	s_mov_b32 s1, 0
	s_waitcnt lgkmcnt(0)
	s_waitcnt lgkmcnt(4)
	v_pk_mul_f32 v[224:225], v[224:225], v[198:199]
	v_pk_mul_f32 v[226:227], v[226:227], v[200:201]
	v_pk_mul_f32 v[228:229], v[228:229], v[202:203]
	v_pk_mul_f32 v[230:231], v[230:231], v[204:205]
	v_mfma_f32_16x16x4_f32 v[36:39], v44, v224, 0
	v_mfma_f32_16x16x4_f32 v[40:43], v45, v225, 0
	v_mfma_f32_16x16x4_f32 v[36:39], v46, v226, v[36:39]
	v_mfma_f32_16x16x4_f32 v[40:43], v47, v227, v[40:43]
	v_pk_mul_f32 v[232:233], v[232:233], v[206:207]
	v_pk_mul_f32 v[234:235], v[234:235], v[208:209]
	v_mfma_f32_16x16x4_f32 v[36:39], v48, v228, v[36:39]
	v_mfma_f32_16x16x4_f32 v[40:43], v49, v229, v[40:43]
	v_mfma_f32_16x16x4_f32 v[36:39], v50, v230, v[36:39]
	v_mfma_f32_16x16x4_f32 v[40:43], v51, v231, v[40:43]
	v_pk_mul_f32 v[236:237], v[236:237], v[210:211]
	v_pk_mul_f32 v[238:239], v[238:239], v[212:213]
	v_mfma_f32_16x16x4_f32 v[36:39], v68, v232, v[36:39]
	v_mfma_f32_16x16x4_f32 v[40:43], v69, v233, v[40:43]
	v_mfma_f32_16x16x4_f32 v[36:39], v70, v234, v[36:39]
	v_mfma_f32_16x16x4_f32 v[40:43], v71, v235, v[40:43]
	v_mfma_f32_16x16x4_f32 v[36:39], v96, v236, v[36:39]
	v_mfma_f32_16x16x4_f32 v[40:43], v97, v237, v[40:43]
	v_mfma_f32_16x16x4_f32 v[36:39], v98, v238, v[36:39]
	v_mfma_f32_16x16x4_f32 v[40:43], v99, v239, v[40:43]
	v_mfma_f32_16x16x4_f32 v[36:39], v216, v214, v[36:39]
	v_mfma_f32_16x16x4_f32 v[40:43], v217, v215, v[40:43]
	ds_read_b128 v[44:47], v168 offset:2176
	ds_read_b128 v[48:51], v168 offset:2240
	ds_read_b128 v[68:71], v168 offset:2304
	ds_read_b128 v[96:99], v168 offset:2368
	ds_read_b32 v216, v171 offset:1024
	ds_read_b32 v217, v171 offset:1040
	ds_read_b128 v[198:201], v174 offset:0
	ds_read_b128 v[202:205], v174 offset:64
	ds_read_b128 v[206:209], v174 offset:128
	ds_read_b128 v[210:213], v174 offset:192
	v_mfma_f32_16x16x4_f32 v[224:227], v190, v214, v[224:227]
	v_mfma_f32_16x16x4_f32 v[224:227], v194, v215, v[224:227]
	v_mfma_f32_16x16x4_f32 v[228:231], v191, v214, v[228:231]
	v_mfma_f32_16x16x4_f32 v[228:231], v195, v215, v[228:231]
	v_mfma_f32_16x16x4_f32 v[232:235], v192, v214, v[232:235]
	v_mfma_f32_16x16x4_f32 v[232:235], v196, v215, v[232:235]
	v_mfma_f32_16x16x4_f32 v[236:239], v193, v214, v[236:239]
	v_mfma_f32_16x16x4_f32 v[236:239], v197, v215, v[236:239]
	ds_read_b32 v214, v169 offset:2048
	ds_read_b32 v215, v169 offset:3072
	v_pk_add_f32 v[80:81], v[36:37], v[40:41]
	v_pk_add_f32 v[82:83], v[38:39], v[42:43]
	v_pk_add_f32 v[84:85], v[36:37], v[40:41]
	v_pk_add_f32 v[86:87], v[38:39], v[42:43]
	v_pk_add_f32 v[36:37], v[36:37], v[40:41]
	v_pk_add_f32 v[38:39], v[38:39], v[42:43]
	v_permlane32_swap_b32_e32 v80, v84
	v_permlane32_swap_b32_e32 v81, v85
	v_permlane32_swap_b32_e32 v82, v86
	v_permlane32_swap_b32_e32 v83, v87
	v_mov_b32_e32 v88, v80
	v_mov_b32_e32 v89, v81
	v_mov_b32_e32 v90, v82
	v_mov_b32_e32 v91, v83
	s_nop 0
	v_permlane16_swap_b32_e32 v80, v88
	v_permlane16_swap_b32_e32 v81, v89
	v_permlane16_swap_b32_e32 v82, v90
	v_permlane16_swap_b32_e32 v83, v91
	v_fmac_f32_e32 v81, v124, v80
	v_fmac_f32_e32 v82, v128, v80
	v_fmac_f32_e32 v83, v132, v80
	v_fmac_f32_e32 v88, v136, v80
	v_fmac_f32_e32 v89, v144, v80
	v_fmac_f32_e32 v90, v152, v80
	v_fmac_f32_e32 v91, v160, v80
	v_fmac_f32_e32 v82, v129, v81
	v_fmac_f32_e32 v83, v133, v81
	v_fmac_f32_e32 v88, v137, v81
	v_fmac_f32_e32 v89, v145, v81
	v_fmac_f32_e32 v90, v153, v81
	v_fmac_f32_e32 v91, v161, v81
	v_fmac_f32_e32 v83, v134, v82
	v_fmac_f32_e32 v88, v138, v82
	v_fmac_f32_e32 v89, v146, v82
	v_fmac_f32_e32 v90, v154, v82
	v_fmac_f32_e32 v91, v162, v82
	v_fmac_f32_e32 v88, v139, v83
	v_fmac_f32_e32 v89, v147, v83
	v_fmac_f32_e32 v90, v155, v83
	v_fmac_f32_e32 v91, v163, v83
	v_fmac_f32_e32 v89, v148, v88
	v_fmac_f32_e32 v90, v156, v88
	v_fmac_f32_e32 v91, v164, v88
	v_fmac_f32_e32 v90, v157, v89
	v_fmac_f32_e32 v91, v165, v89
	v_fmac_f32_e32 v91, v166, v90
	ds_read_b128 v[124:127], v170 offset:1056
	ds_read_b128 v[128:131], v170 offset:1088
	ds_read_b128 v[132:135], v170 offset:1120
	ds_read_b128 v[136:139], v170 offset:1152
	ds_read_b128 v[144:147], v170 offset:1184
	ds_read_b128 v[148:151], v170 offset:1200
	ds_read_b128 v[152:155], v170 offset:1216
	ds_read_b128 v[156:159], v170 offset:1232
	ds_read_b128 v[160:163], v170 offset:1248
	ds_read_b128 v[164:167], v170 offset:1264
	v_cndmask_b32_e32 v220, v80, v81, vcc
	v_cndmask_b32_e64 v220, v220, v82, s[4:5]
	v_cndmask_b32_e64 v220, v220, v83, s[6:7]
	v_cndmask_b32_e32 v221, v88, v89, vcc
	v_cndmask_b32_e64 v221, v221, v90, s[4:5]
	v_cndmask_b32_e64 v221, v221, v91, s[6:7]
	s_nop 1
	v_mfma_f32_16x16x4_f32 v[84:87], v218, v220, v[36:39]
	v_mfma_f32_16x16x4_f32 v[84:87], v219, v221, v[84:87]
	ds_read_b32 v218, v172 offset:1024
	ds_read_b32 v219, v172 offset:1040
	v_mfma_f32_16x16x4_f32 v[224:227], v182, v220, v[224:227]
	v_mfma_f32_16x16x4_f32 v[224:227], v186, v221, v[224:227]
	v_mfma_f32_16x16x4_f32 v[228:231], v183, v220, v[228:231]
	v_mfma_f32_16x16x4_f32 v[228:231], v187, v221, v[228:231]
	v_mfma_f32_16x16x4_f32 v[232:235], v184, v220, v[232:235]
	v_mfma_f32_16x16x4_f32 v[232:235], v188, v221, v[232:235]
	v_mfma_f32_16x16x4_f32 v[236:239], v185, v220, v[236:239]
	v_mfma_f32_16x16x4_f32 v[236:239], v189, v221, v[236:239]
	v_add_u32_e32 v173, 0x880, v173
	v_add_u32_e32 v2, 0x880, v2
	v_add_u32_e32 v3, 0x880, v3
	v_add_u32_e32 v5, 0x880, v5
	ds_read2_b32 v[182:183], v173 offset0:0 offset1:16
	ds_read2_b32 v[184:185], v173 offset0:32 offset1:48
	ds_read2_b32 v[186:187], v2 offset0:0 offset1:16
	ds_read2_b32 v[188:189], v2 offset0:32 offset1:48
	ds_read2_b32 v[190:191], v3 offset0:0 offset1:16
	ds_read2_b32 v[192:193], v3 offset0:32 offset1:48
	ds_read2_b32 v[194:195], v5 offset0:0 offset1:16
	ds_read2_b32 v[196:197], v5 offset0:32 offset1:48
	s_mov_b64 exec, s[8:9]
	ds_write_b32 v175, v84 offset:0
	ds_write_b32 v175, v85 offset:256
	ds_write_b32 v175, v86 offset:512
	ds_write_b32 v175, v87 offset:768
	s_mov_b64 exec, -1
	s_waitcnt lgkmcnt(4)
	v_pk_mul_f32 v[224:225], v[224:225], v[198:199]
	v_pk_mul_f32 v[226:227], v[226:227], v[200:201]
	v_pk_mul_f32 v[228:229], v[228:229], v[202:203]
	v_pk_mul_f32 v[230:231], v[230:231], v[204:205]
	v_mfma_f32_16x16x4_f32 v[36:39], v44, v224, 0
	v_mfma_f32_16x16x4_f32 v[40:43], v45, v225, 0
	v_mfma_f32_16x16x4_f32 v[36:39], v46, v226, v[36:39]
	v_mfma_f32_16x16x4_f32 v[40:43], v47, v227, v[40:43]
	v_pk_mul_f32 v[232:233], v[232:233], v[206:207]
	v_pk_mul_f32 v[234:235], v[234:235], v[208:209]
	v_mfma_f32_16x16x4_f32 v[36:39], v48, v228, v[36:39]
	v_mfma_f32_16x16x4_f32 v[40:43], v49, v229, v[40:43]
	v_mfma_f32_16x16x4_f32 v[36:39], v50, v230, v[36:39]
	v_mfma_f32_16x16x4_f32 v[40:43], v51, v231, v[40:43]
	v_pk_mul_f32 v[236:237], v[236:237], v[210:211]
	v_pk_mul_f32 v[238:239], v[238:239], v[212:213]
	v_mfma_f32_16x16x4_f32 v[36:39], v68, v232, v[36:39]
	v_mfma_f32_16x16x4_f32 v[40:43], v69, v233, v[40:43]
	v_mfma_f32_16x16x4_f32 v[36:39], v70, v234, v[36:39]
	v_mfma_f32_16x16x4_f32 v[40:43], v71, v235, v[40:43]
	v_mfma_f32_16x16x4_f32 v[36:39], v96, v236, v[36:39]
	v_mfma_f32_16x16x4_f32 v[40:43], v97, v237, v[40:43]
	v_mfma_f32_16x16x4_f32 v[36:39], v98, v238, v[36:39]
	v_mfma_f32_16x16x4_f32 v[40:43], v99, v239, v[40:43]
	v_mfma_f32_16x16x4_f32 v[36:39], v216, v214, v[36:39]
	v_mfma_f32_16x16x4_f32 v[40:43], v217, v215, v[40:43]
	s_waitcnt lgkmcnt(0)
	s_barrier
	ds_read_b128 v[44:47], v168 offset:4352
	ds_read_b128 v[48:51], v168 offset:4416
	ds_read_b128 v[68:71], v168 offset:4480
	ds_read_b128 v[96:99], v168 offset:4544
	ds_read_b32 v216, v171 offset:2048
	ds_read_b32 v217, v171 offset:2064
	ds_read_b128 v[198:201], v174 offset:256
	ds_read_b128 v[202:205], v174 offset:320
	ds_read_b128 v[206:209], v174 offset:384
	ds_read_b128 v[210:213], v174 offset:448
	v_mfma_f32_16x16x4_f32 v[224:227], v190, v214, v[224:227]
	v_mfma_f32_16x16x4_f32 v[224:227], v194, v215, v[224:227]
	v_mfma_f32_16x16x4_f32 v[228:231], v191, v214, v[228:231]
	v_mfma_f32_16x16x4_f32 v[228:231], v195, v215, v[228:231]
	v_mfma_f32_16x16x4_f32 v[232:235], v192, v214, v[232:235]
	v_mfma_f32_16x16x4_f32 v[232:235], v196, v215, v[232:235]
	v_mfma_f32_16x16x4_f32 v[236:239], v193, v214, v[236:239]
	v_mfma_f32_16x16x4_f32 v[236:239], v197, v215, v[236:239]
	ds_read_b32 v214, v169 offset:4096
	ds_read_b32 v215, v169 offset:5120
	v_pk_add_f32 v[80:81], v[36:37], v[40:41]
	v_pk_add_f32 v[82:83], v[38:39], v[42:43]
	v_pk_add_f32 v[84:85], v[36:37], v[40:41]
	v_pk_add_f32 v[86:87], v[38:39], v[42:43]
	v_pk_add_f32 v[36:37], v[36:37], v[40:41]
	v_pk_add_f32 v[38:39], v[38:39], v[42:43]
	v_permlane32_swap_b32_e32 v80, v84
	v_permlane32_swap_b32_e32 v81, v85
	v_permlane32_swap_b32_e32 v82, v86
	v_permlane32_swap_b32_e32 v83, v87
	v_mov_b32_e32 v88, v80
	v_mov_b32_e32 v89, v81
	v_mov_b32_e32 v90, v82
	v_mov_b32_e32 v91, v83
	s_nop 0
	v_permlane16_swap_b32_e32 v80, v88
	v_permlane16_swap_b32_e32 v81, v89
	v_permlane16_swap_b32_e32 v82, v90
	v_permlane16_swap_b32_e32 v83, v91
	v_fmac_f32_e32 v81, v124, v80
	v_fmac_f32_e32 v82, v128, v80
	v_fmac_f32_e32 v83, v132, v80
	v_fmac_f32_e32 v88, v136, v80
	v_fmac_f32_e32 v89, v144, v80
	v_fmac_f32_e32 v90, v152, v80
	v_fmac_f32_e32 v91, v160, v80
	v_fmac_f32_e32 v82, v129, v81
	v_fmac_f32_e32 v83, v133, v81
	v_fmac_f32_e32 v88, v137, v81
	v_fmac_f32_e32 v89, v145, v81
	v_fmac_f32_e32 v90, v153, v81
	v_fmac_f32_e32 v91, v161, v81
	v_fmac_f32_e32 v83, v134, v82
	v_fmac_f32_e32 v88, v138, v82
	v_fmac_f32_e32 v89, v146, v82
	v_fmac_f32_e32 v90, v154, v82
	v_fmac_f32_e32 v91, v162, v82
	v_fmac_f32_e32 v88, v139, v83
	v_fmac_f32_e32 v89, v147, v83
	v_fmac_f32_e32 v90, v155, v83
	v_fmac_f32_e32 v91, v163, v83
	v_fmac_f32_e32 v89, v148, v88
	v_fmac_f32_e32 v90, v156, v88
	v_fmac_f32_e32 v91, v164, v88
	v_fmac_f32_e32 v90, v157, v89
	v_fmac_f32_e32 v91, v165, v89
	v_fmac_f32_e32 v91, v166, v90
	ds_read_b128 v[124:127], v170 offset:2080
	ds_read_b128 v[128:131], v170 offset:2112
	ds_read_b128 v[132:135], v170 offset:2144
	ds_read_b128 v[136:139], v170 offset:2176
	ds_read_b128 v[144:147], v170 offset:2208
	ds_read_b128 v[148:151], v170 offset:2224
	ds_read_b128 v[152:155], v170 offset:2240
	ds_read_b128 v[156:159], v170 offset:2256
	ds_read_b128 v[160:163], v170 offset:2272
	ds_read_b128 v[164:167], v170 offset:2288
	v_cndmask_b32_e32 v220, v80, v81, vcc
	v_cndmask_b32_e64 v220, v220, v82, s[4:5]
	v_cndmask_b32_e64 v220, v220, v83, s[6:7]
	v_cndmask_b32_e32 v221, v88, v89, vcc
	v_cndmask_b32_e64 v221, v221, v90, s[4:5]
	v_cndmask_b32_e64 v221, v221, v91, s[6:7]
	s_nop 1
	v_mfma_f32_16x16x4_f32 v[84:87], v218, v220, v[36:39]
	v_mfma_f32_16x16x4_f32 v[84:87], v219, v221, v[84:87]
	ds_read_b32 v218, v172 offset:2048
	ds_read_b32 v219, v172 offset:2064
	v_mfma_f32_16x16x4_f32 v[224:227], v182, v220, v[224:227]
	v_mfma_f32_16x16x4_f32 v[224:227], v186, v221, v[224:227]
	v_mfma_f32_16x16x4_f32 v[228:231], v183, v220, v[228:231]
	v_mfma_f32_16x16x4_f32 v[228:231], v187, v221, v[228:231]
	v_mfma_f32_16x16x4_f32 v[232:235], v184, v220, v[232:235]
	v_mfma_f32_16x16x4_f32 v[232:235], v188, v221, v[232:235]
	v_mfma_f32_16x16x4_f32 v[236:239], v185, v220, v[236:239]
	v_mfma_f32_16x16x4_f32 v[236:239], v189, v221, v[236:239]
	v_add_u32_e32 v173, 0x880, v173
	v_add_u32_e32 v2, 0x880, v2
	v_add_u32_e32 v3, 0x880, v3
	v_add_u32_e32 v5, 0x880, v5
	ds_read2_b32 v[182:183], v173 offset0:0 offset1:16
	ds_read2_b32 v[184:185], v173 offset0:32 offset1:48
	ds_read2_b32 v[186:187], v2 offset0:0 offset1:16
	ds_read2_b32 v[188:189], v2 offset0:32 offset1:48
	ds_read2_b32 v[190:191], v3 offset0:0 offset1:16
	ds_read2_b32 v[192:193], v3 offset0:32 offset1:48
	ds_read2_b32 v[194:195], v5 offset0:0 offset1:16
	ds_read2_b32 v[196:197], v5 offset0:32 offset1:48
	s_mov_b64 exec, s[8:9]
	ds_write_b32 v175, v84 offset:2048
	ds_write_b32 v175, v85 offset:2304
	ds_write_b32 v175, v86 offset:2560
	ds_write_b32 v175, v87 offset:2816
	s_mov_b64 exec, -1
	s_waitcnt lgkmcnt(4)
	v_pk_mul_f32 v[224:225], v[224:225], v[198:199]
	v_pk_mul_f32 v[226:227], v[226:227], v[200:201]
	v_pk_mul_f32 v[228:229], v[228:229], v[202:203]
	v_pk_mul_f32 v[230:231], v[230:231], v[204:205]
	v_mfma_f32_16x16x4_f32 v[36:39], v44, v224, 0
	v_mfma_f32_16x16x4_f32 v[40:43], v45, v225, 0
	v_mfma_f32_16x16x4_f32 v[36:39], v46, v226, v[36:39]
	v_mfma_f32_16x16x4_f32 v[40:43], v47, v227, v[40:43]
	v_pk_mul_f32 v[232:233], v[232:233], v[206:207]
	v_pk_mul_f32 v[234:235], v[234:235], v[208:209]
	v_mfma_f32_16x16x4_f32 v[36:39], v48, v228, v[36:39]
	v_mfma_f32_16x16x4_f32 v[40:43], v49, v229, v[40:43]
	v_mfma_f32_16x16x4_f32 v[36:39], v50, v230, v[36:39]
	v_mfma_f32_16x16x4_f32 v[40:43], v51, v231, v[40:43]
	v_pk_mul_f32 v[236:237], v[236:237], v[210:211]
	v_pk_mul_f32 v[238:239], v[238:239], v[212:213]
	v_mfma_f32_16x16x4_f32 v[36:39], v68, v232, v[36:39]
	v_mfma_f32_16x16x4_f32 v[40:43], v69, v233, v[40:43]
	v_mfma_f32_16x16x4_f32 v[36:39], v70, v234, v[36:39]
	v_mfma_f32_16x16x4_f32 v[40:43], v71, v235, v[40:43]
	v_mfma_f32_16x16x4_f32 v[36:39], v96, v236, v[36:39]
	v_mfma_f32_16x16x4_f32 v[40:43], v97, v237, v[40:43]
	v_mfma_f32_16x16x4_f32 v[36:39], v98, v238, v[36:39]
	v_mfma_f32_16x16x4_f32 v[40:43], v99, v239, v[40:43]
	v_mfma_f32_16x16x4_f32 v[36:39], v216, v214, v[36:39]
	v_mfma_f32_16x16x4_f32 v[40:43], v217, v215, v[40:43]
	s_waitcnt lgkmcnt(0)
	s_barrier
	ds_read_b128 v[44:47], v168 offset:6528
	ds_read_b128 v[48:51], v168 offset:6592
	ds_read_b128 v[68:71], v168 offset:6656
	ds_read_b128 v[96:99], v168 offset:6720
	ds_read_b32 v216, v171 offset:3072
	ds_read_b32 v217, v171 offset:3088
	ds_read_b128 v[198:201], v174 offset:512
	ds_read_b128 v[202:205], v174 offset:576
	ds_read_b128 v[206:209], v174 offset:640
	ds_read_b128 v[210:213], v174 offset:704
	v_mfma_f32_16x16x4_f32 v[224:227], v190, v214, v[224:227]
	v_mfma_f32_16x16x4_f32 v[224:227], v194, v215, v[224:227]
	v_mfma_f32_16x16x4_f32 v[228:231], v191, v214, v[228:231]
	v_mfma_f32_16x16x4_f32 v[228:231], v195, v215, v[228:231]
	v_mfma_f32_16x16x4_f32 v[232:235], v192, v214, v[232:235]
	v_mfma_f32_16x16x4_f32 v[232:235], v196, v215, v[232:235]
	v_mfma_f32_16x16x4_f32 v[236:239], v193, v214, v[236:239]
	v_mfma_f32_16x16x4_f32 v[236:239], v197, v215, v[236:239]
	ds_read_b32 v214, v169 offset:6144
	ds_read_b32 v215, v169 offset:7168
	v_pk_add_f32 v[80:81], v[36:37], v[40:41]
	v_pk_add_f32 v[82:83], v[38:39], v[42:43]
	v_pk_add_f32 v[84:85], v[36:37], v[40:41]
	v_pk_add_f32 v[86:87], v[38:39], v[42:43]
	v_pk_add_f32 v[36:37], v[36:37], v[40:41]
	v_pk_add_f32 v[38:39], v[38:39], v[42:43]
	v_permlane32_swap_b32_e32 v80, v84
	v_permlane32_swap_b32_e32 v81, v85
	v_permlane32_swap_b32_e32 v82, v86
	v_permlane32_swap_b32_e32 v83, v87
	v_mov_b32_e32 v88, v80
	v_mov_b32_e32 v89, v81
	v_mov_b32_e32 v90, v82
	v_mov_b32_e32 v91, v83
	s_nop 0
	v_permlane16_swap_b32_e32 v80, v88
	v_permlane16_swap_b32_e32 v81, v89
	v_permlane16_swap_b32_e32 v82, v90
	v_permlane16_swap_b32_e32 v83, v91
	v_fmac_f32_e32 v81, v124, v80
	v_fmac_f32_e32 v82, v128, v80
	v_fmac_f32_e32 v83, v132, v80
	v_fmac_f32_e32 v88, v136, v80
	v_fmac_f32_e32 v89, v144, v80
	v_fmac_f32_e32 v90, v152, v80
	v_fmac_f32_e32 v91, v160, v80
	v_fmac_f32_e32 v82, v129, v81
	v_fmac_f32_e32 v83, v133, v81
	v_fmac_f32_e32 v88, v137, v81
	v_fmac_f32_e32 v89, v145, v81
	v_fmac_f32_e32 v90, v153, v81
	v_fmac_f32_e32 v91, v161, v81
	v_fmac_f32_e32 v83, v134, v82
	v_fmac_f32_e32 v88, v138, v82
	v_fmac_f32_e32 v89, v146, v82
	v_fmac_f32_e32 v90, v154, v82
	v_fmac_f32_e32 v91, v162, v82
	v_fmac_f32_e32 v88, v139, v83
	v_fmac_f32_e32 v89, v147, v83
	v_fmac_f32_e32 v90, v155, v83
	v_fmac_f32_e32 v91, v163, v83
	v_fmac_f32_e32 v89, v148, v88
	v_fmac_f32_e32 v90, v156, v88
	v_fmac_f32_e32 v91, v164, v88
	v_fmac_f32_e32 v90, v157, v89
	v_fmac_f32_e32 v91, v165, v89
	v_fmac_f32_e32 v91, v166, v90
	ds_read_b128 v[124:127], v170 offset:3104
	ds_read_b128 v[128:131], v170 offset:3136
	ds_read_b128 v[132:135], v170 offset:3168
	ds_read_b128 v[136:139], v170 offset:3200
	ds_read_b128 v[144:147], v170 offset:3232
	ds_read_b128 v[148:151], v170 offset:3248
	ds_read_b128 v[152:155], v170 offset:3264
	ds_read_b128 v[156:159], v170 offset:3280
	ds_read_b128 v[160:163], v170 offset:3296
	ds_read_b128 v[164:167], v170 offset:3312
	v_cndmask_b32_e32 v220, v80, v81, vcc
	v_cndmask_b32_e64 v220, v220, v82, s[4:5]
	v_cndmask_b32_e64 v220, v220, v83, s[6:7]
	v_cndmask_b32_e32 v221, v88, v89, vcc
	v_cndmask_b32_e64 v221, v221, v90, s[4:5]
	v_cndmask_b32_e64 v221, v221, v91, s[6:7]
	s_nop 1
	v_mfma_f32_16x16x4_f32 v[84:87], v218, v220, v[36:39]
	v_mfma_f32_16x16x4_f32 v[84:87], v219, v221, v[84:87]
	ds_read_b32 v218, v172 offset:3072
	ds_read_b32 v219, v172 offset:3088
	v_mfma_f32_16x16x4_f32 v[224:227], v182, v220, v[224:227]
	v_mfma_f32_16x16x4_f32 v[224:227], v186, v221, v[224:227]
	v_mfma_f32_16x16x4_f32 v[228:231], v183, v220, v[228:231]
	v_mfma_f32_16x16x4_f32 v[228:231], v187, v221, v[228:231]
	v_mfma_f32_16x16x4_f32 v[232:235], v184, v220, v[232:235]
	v_mfma_f32_16x16x4_f32 v[232:235], v188, v221, v[232:235]
	v_mfma_f32_16x16x4_f32 v[236:239], v185, v220, v[236:239]
	v_mfma_f32_16x16x4_f32 v[236:239], v189, v221, v[236:239]
	v_add_u32_e32 v173, 0x880, v173
	v_add_u32_e32 v2, 0x880, v2
	v_add_u32_e32 v3, 0x880, v3
	v_add_u32_e32 v5, 0x880, v5
	ds_read2_b32 v[182:183], v173 offset0:0 offset1:16
	ds_read2_b32 v[184:185], v173 offset0:32 offset1:48
	ds_read2_b32 v[186:187], v2 offset0:0 offset1:16
	ds_read2_b32 v[188:189], v2 offset0:32 offset1:48
	ds_read2_b32 v[190:191], v3 offset0:0 offset1:16
	ds_read2_b32 v[192:193], v3 offset0:32 offset1:48
	ds_read2_b32 v[194:195], v5 offset0:0 offset1:16
	ds_read2_b32 v[196:197], v5 offset0:32 offset1:48
	s_mov_b64 exec, s[8:9]
	ds_write_b32 v175, v84 offset:4096
	ds_write_b32 v175, v85 offset:4352
	ds_write_b32 v175, v86 offset:4608
	ds_write_b32 v175, v87 offset:4864
	s_mov_b64 exec, -1
	s_waitcnt lgkmcnt(4)
	v_pk_mul_f32 v[224:225], v[224:225], v[198:199]
	v_pk_mul_f32 v[226:227], v[226:227], v[200:201]
	v_pk_mul_f32 v[228:229], v[228:229], v[202:203]
	v_pk_mul_f32 v[230:231], v[230:231], v[204:205]
	v_mfma_f32_16x16x4_f32 v[36:39], v44, v224, 0
	v_mfma_f32_16x16x4_f32 v[40:43], v45, v225, 0
	v_mfma_f32_16x16x4_f32 v[36:39], v46, v226, v[36:39]
	v_mfma_f32_16x16x4_f32 v[40:43], v47, v227, v[40:43]
	v_pk_mul_f32 v[232:233], v[232:233], v[206:207]
	v_pk_mul_f32 v[234:235], v[234:235], v[208:209]
	v_mfma_f32_16x16x4_f32 v[36:39], v48, v228, v[36:39]
	v_mfma_f32_16x16x4_f32 v[40:43], v49, v229, v[40:43]
	v_mfma_f32_16x16x4_f32 v[36:39], v50, v230, v[36:39]
	v_mfma_f32_16x16x4_f32 v[40:43], v51, v231, v[40:43]
	v_pk_mul_f32 v[236:237], v[236:237], v[210:211]
	v_pk_mul_f32 v[238:239], v[238:239], v[212:213]
	v_mfma_f32_16x16x4_f32 v[36:39], v68, v232, v[36:39]
	v_mfma_f32_16x16x4_f32 v[40:43], v69, v233, v[40:43]
	v_mfma_f32_16x16x4_f32 v[36:39], v70, v234, v[36:39]
	v_mfma_f32_16x16x4_f32 v[40:43], v71, v235, v[40:43]
	v_mfma_f32_16x16x4_f32 v[36:39], v96, v236, v[36:39]
	v_mfma_f32_16x16x4_f32 v[40:43], v97, v237, v[40:43]
	v_mfma_f32_16x16x4_f32 v[36:39], v98, v238, v[36:39]
	v_mfma_f32_16x16x4_f32 v[40:43], v99, v239, v[40:43]
	v_mfma_f32_16x16x4_f32 v[36:39], v216, v214, v[36:39]
	v_mfma_f32_16x16x4_f32 v[40:43], v217, v215, v[40:43]
	s_waitcnt lgkmcnt(0)
	s_barrier
	ds_read_b128 v[44:47], v168 offset:8704
	ds_read_b128 v[48:51], v168 offset:8768
	ds_read_b128 v[68:71], v168 offset:8832
	ds_read_b128 v[96:99], v168 offset:8896
	ds_read_b32 v216, v171 offset:4096
	ds_read_b32 v217, v171 offset:4112
	ds_read_b128 v[198:201], v174 offset:768
	ds_read_b128 v[202:205], v174 offset:832
	ds_read_b128 v[206:209], v174 offset:896
	ds_read_b128 v[210:213], v174 offset:960
	v_mfma_f32_16x16x4_f32 v[224:227], v190, v214, v[224:227]
	v_mfma_f32_16x16x4_f32 v[224:227], v194, v215, v[224:227]
	v_mfma_f32_16x16x4_f32 v[228:231], v191, v214, v[228:231]
	v_mfma_f32_16x16x4_f32 v[228:231], v195, v215, v[228:231]
	v_mfma_f32_16x16x4_f32 v[232:235], v192, v214, v[232:235]
	v_mfma_f32_16x16x4_f32 v[232:235], v196, v215, v[232:235]
	v_mfma_f32_16x16x4_f32 v[236:239], v193, v214, v[236:239]
	v_mfma_f32_16x16x4_f32 v[236:239], v197, v215, v[236:239]
	ds_read_b32 v214, v169 offset:8192
	ds_read_b32 v215, v169 offset:9216
	v_pk_add_f32 v[80:81], v[36:37], v[40:41]
	v_pk_add_f32 v[82:83], v[38:39], v[42:43]
	v_pk_add_f32 v[84:85], v[36:37], v[40:41]
	v_pk_add_f32 v[86:87], v[38:39], v[42:43]
	v_pk_add_f32 v[36:37], v[36:37], v[40:41]
	v_pk_add_f32 v[38:39], v[38:39], v[42:43]
	v_permlane32_swap_b32_e32 v80, v84
	v_permlane32_swap_b32_e32 v81, v85
	v_permlane32_swap_b32_e32 v82, v86
	v_permlane32_swap_b32_e32 v83, v87
	v_mov_b32_e32 v88, v80
	v_mov_b32_e32 v89, v81
	v_mov_b32_e32 v90, v82
	v_mov_b32_e32 v91, v83
	s_nop 0
	v_permlane16_swap_b32_e32 v80, v88
	v_permlane16_swap_b32_e32 v81, v89
	v_permlane16_swap_b32_e32 v82, v90
	v_permlane16_swap_b32_e32 v83, v91
	v_fmac_f32_e32 v81, v124, v80
	v_fmac_f32_e32 v82, v128, v80
	v_fmac_f32_e32 v83, v132, v80
	v_fmac_f32_e32 v88, v136, v80
	v_fmac_f32_e32 v89, v144, v80
	v_fmac_f32_e32 v90, v152, v80
	v_fmac_f32_e32 v91, v160, v80
	v_fmac_f32_e32 v82, v129, v81
	v_fmac_f32_e32 v83, v133, v81
	v_fmac_f32_e32 v88, v137, v81
	v_fmac_f32_e32 v89, v145, v81
	v_fmac_f32_e32 v90, v153, v81
	v_fmac_f32_e32 v91, v161, v81
	v_fmac_f32_e32 v83, v134, v82
	v_fmac_f32_e32 v88, v138, v82
	v_fmac_f32_e32 v89, v146, v82
	v_fmac_f32_e32 v90, v154, v82
	v_fmac_f32_e32 v91, v162, v82
	v_fmac_f32_e32 v88, v139, v83
	v_fmac_f32_e32 v89, v147, v83
	v_fmac_f32_e32 v90, v155, v83
	v_fmac_f32_e32 v91, v163, v83
	v_fmac_f32_e32 v89, v148, v88
	v_fmac_f32_e32 v90, v156, v88
	v_fmac_f32_e32 v91, v164, v88
	v_fmac_f32_e32 v90, v157, v89
	v_fmac_f32_e32 v91, v165, v89
	v_fmac_f32_e32 v91, v166, v90
	ds_read_b128 v[124:127], v170 offset:4128
	ds_read_b128 v[128:131], v170 offset:4160
	ds_read_b128 v[132:135], v170 offset:4192
	ds_read_b128 v[136:139], v170 offset:4224
	ds_read_b128 v[144:147], v170 offset:4256
	ds_read_b128 v[148:151], v170 offset:4272
	ds_read_b128 v[152:155], v170 offset:4288
	ds_read_b128 v[156:159], v170 offset:4304
	ds_read_b128 v[160:163], v170 offset:4320
	ds_read_b128 v[164:167], v170 offset:4336
	v_cndmask_b32_e32 v220, v80, v81, vcc
	v_cndmask_b32_e64 v220, v220, v82, s[4:5]
	v_cndmask_b32_e64 v220, v220, v83, s[6:7]
	v_cndmask_b32_e32 v221, v88, v89, vcc
	v_cndmask_b32_e64 v221, v221, v90, s[4:5]
	v_cndmask_b32_e64 v221, v221, v91, s[6:7]
	s_nop 1
	v_mfma_f32_16x16x4_f32 v[84:87], v218, v220, v[36:39]
	v_mfma_f32_16x16x4_f32 v[84:87], v219, v221, v[84:87]
	ds_read_b32 v218, v172 offset:4096
	ds_read_b32 v219, v172 offset:4112
	v_mfma_f32_16x16x4_f32 v[224:227], v182, v220, v[224:227]
	v_mfma_f32_16x16x4_f32 v[224:227], v186, v221, v[224:227]
	v_mfma_f32_16x16x4_f32 v[228:231], v183, v220, v[228:231]
	v_mfma_f32_16x16x4_f32 v[228:231], v187, v221, v[228:231]
	v_mfma_f32_16x16x4_f32 v[232:235], v184, v220, v[232:235]
	v_mfma_f32_16x16x4_f32 v[232:235], v188, v221, v[232:235]
	v_mfma_f32_16x16x4_f32 v[236:239], v185, v220, v[236:239]
	v_mfma_f32_16x16x4_f32 v[236:239], v189, v221, v[236:239]
	v_add_u32_e32 v173, 0x880, v173
	v_add_u32_e32 v2, 0x880, v2
	v_add_u32_e32 v3, 0x880, v3
	v_add_u32_e32 v5, 0x880, v5
	ds_read2_b32 v[182:183], v173 offset0:0 offset1:16
	ds_read2_b32 v[184:185], v173 offset0:32 offset1:48
	ds_read2_b32 v[186:187], v2 offset0:0 offset1:16
	ds_read2_b32 v[188:189], v2 offset0:32 offset1:48
	ds_read2_b32 v[190:191], v3 offset0:0 offset1:16
	ds_read2_b32 v[192:193], v3 offset0:32 offset1:48
	ds_read2_b32 v[194:195], v5 offset0:0 offset1:16
	ds_read2_b32 v[196:197], v5 offset0:32 offset1:48
	s_mov_b64 exec, s[8:9]
	ds_write_b32 v175, v84 offset:6144
	ds_write_b32 v175, v85 offset:6400
	ds_write_b32 v175, v86 offset:6656
	ds_write_b32 v175, v87 offset:6912
	s_mov_b64 exec, -1
	s_waitcnt lgkmcnt(4)
	v_pk_mul_f32 v[224:225], v[224:225], v[198:199]
	v_pk_mul_f32 v[226:227], v[226:227], v[200:201]
	v_pk_mul_f32 v[228:229], v[228:229], v[202:203]
	v_pk_mul_f32 v[230:231], v[230:231], v[204:205]
	v_mfma_f32_16x16x4_f32 v[36:39], v44, v224, 0
	v_mfma_f32_16x16x4_f32 v[40:43], v45, v225, 0
	v_mfma_f32_16x16x4_f32 v[36:39], v46, v226, v[36:39]
	v_mfma_f32_16x16x4_f32 v[40:43], v47, v227, v[40:43]
	v_pk_mul_f32 v[232:233], v[232:233], v[206:207]
	v_pk_mul_f32 v[234:235], v[234:235], v[208:209]
	v_mfma_f32_16x16x4_f32 v[36:39], v48, v228, v[36:39]
	v_mfma_f32_16x16x4_f32 v[40:43], v49, v229, v[40:43]
	v_mfma_f32_16x16x4_f32 v[36:39], v50, v230, v[36:39]
	v_mfma_f32_16x16x4_f32 v[40:43], v51, v231, v[40:43]
	v_pk_mul_f32 v[236:237], v[236:237], v[210:211]
	v_pk_mul_f32 v[238:239], v[238:239], v[212:213]
	v_mfma_f32_16x16x4_f32 v[36:39], v68, v232, v[36:39]
	v_mfma_f32_16x16x4_f32 v[40:43], v69, v233, v[40:43]
	v_mfma_f32_16x16x4_f32 v[36:39], v70, v234, v[36:39]
	v_mfma_f32_16x16x4_f32 v[40:43], v71, v235, v[40:43]
	v_mfma_f32_16x16x4_f32 v[36:39], v96, v236, v[36:39]
	v_mfma_f32_16x16x4_f32 v[40:43], v97, v237, v[40:43]
	v_mfma_f32_16x16x4_f32 v[36:39], v98, v238, v[36:39]
	v_mfma_f32_16x16x4_f32 v[40:43], v99, v239, v[40:43]
	v_mfma_f32_16x16x4_f32 v[36:39], v216, v214, v[36:39]
	v_mfma_f32_16x16x4_f32 v[40:43], v217, v215, v[40:43]
	s_waitcnt lgkmcnt(0)
	s_barrier
	ds_read_b128 v[44:47], v168 offset:10880
	ds_read_b128 v[48:51], v168 offset:10944
	ds_read_b128 v[68:71], v168 offset:11008
	ds_read_b128 v[96:99], v168 offset:11072
	ds_read_b32 v216, v171 offset:5120
	ds_read_b32 v217, v171 offset:5136
	ds_read_b128 v[198:201], v174 offset:1024
	ds_read_b128 v[202:205], v174 offset:1088
	ds_read_b128 v[206:209], v174 offset:1152
	ds_read_b128 v[210:213], v174 offset:1216
	v_mfma_f32_16x16x4_f32 v[224:227], v190, v214, v[224:227]
	v_mfma_f32_16x16x4_f32 v[224:227], v194, v215, v[224:227]
	v_mfma_f32_16x16x4_f32 v[228:231], v191, v214, v[228:231]
	v_mfma_f32_16x16x4_f32 v[228:231], v195, v215, v[228:231]
	v_mfma_f32_16x16x4_f32 v[232:235], v192, v214, v[232:235]
	v_mfma_f32_16x16x4_f32 v[232:235], v196, v215, v[232:235]
	v_mfma_f32_16x16x4_f32 v[236:239], v193, v214, v[236:239]
	v_mfma_f32_16x16x4_f32 v[236:239], v197, v215, v[236:239]
	ds_read_b32 v214, v169 offset:10240
	ds_read_b32 v215, v169 offset:11264
	v_pk_add_f32 v[80:81], v[36:37], v[40:41]
	v_pk_add_f32 v[82:83], v[38:39], v[42:43]
	v_pk_add_f32 v[84:85], v[36:37], v[40:41]
	v_pk_add_f32 v[86:87], v[38:39], v[42:43]
	v_pk_add_f32 v[36:37], v[36:37], v[40:41]
	v_pk_add_f32 v[38:39], v[38:39], v[42:43]
	v_permlane32_swap_b32_e32 v80, v84
	v_permlane32_swap_b32_e32 v81, v85
	v_permlane32_swap_b32_e32 v82, v86
	v_permlane32_swap_b32_e32 v83, v87
	v_mov_b32_e32 v88, v80
	v_mov_b32_e32 v89, v81
	v_mov_b32_e32 v90, v82
	v_mov_b32_e32 v91, v83
	s_nop 0
	v_permlane16_swap_b32_e32 v80, v88
	v_permlane16_swap_b32_e32 v81, v89
	v_permlane16_swap_b32_e32 v82, v90
	v_permlane16_swap_b32_e32 v83, v91
	v_fmac_f32_e32 v81, v124, v80
	v_fmac_f32_e32 v82, v128, v80
	v_fmac_f32_e32 v83, v132, v80
	v_fmac_f32_e32 v88, v136, v80
	v_fmac_f32_e32 v89, v144, v80
	v_fmac_f32_e32 v90, v152, v80
	v_fmac_f32_e32 v91, v160, v80
	v_fmac_f32_e32 v82, v129, v81
	v_fmac_f32_e32 v83, v133, v81
	v_fmac_f32_e32 v88, v137, v81
	v_fmac_f32_e32 v89, v145, v81
	v_fmac_f32_e32 v90, v153, v81
	v_fmac_f32_e32 v91, v161, v81
	v_fmac_f32_e32 v83, v134, v82
	v_fmac_f32_e32 v88, v138, v82
	v_fmac_f32_e32 v89, v146, v82
	v_fmac_f32_e32 v90, v154, v82
	v_fmac_f32_e32 v91, v162, v82
	v_fmac_f32_e32 v88, v139, v83
	v_fmac_f32_e32 v89, v147, v83
	v_fmac_f32_e32 v90, v155, v83
	v_fmac_f32_e32 v91, v163, v83
	v_fmac_f32_e32 v89, v148, v88
	v_fmac_f32_e32 v90, v156, v88
	v_fmac_f32_e32 v91, v164, v88
	v_fmac_f32_e32 v90, v157, v89
	v_fmac_f32_e32 v91, v165, v89
	v_fmac_f32_e32 v91, v166, v90
	ds_read_b128 v[124:127], v170 offset:5152
	ds_read_b128 v[128:131], v170 offset:5184
	ds_read_b128 v[132:135], v170 offset:5216
	ds_read_b128 v[136:139], v170 offset:5248
	ds_read_b128 v[144:147], v170 offset:5280
	ds_read_b128 v[148:151], v170 offset:5296
	ds_read_b128 v[152:155], v170 offset:5312
	ds_read_b128 v[156:159], v170 offset:5328
	ds_read_b128 v[160:163], v170 offset:5344
	ds_read_b128 v[164:167], v170 offset:5360
	v_cndmask_b32_e32 v220, v80, v81, vcc
	v_cndmask_b32_e64 v220, v220, v82, s[4:5]
	v_cndmask_b32_e64 v220, v220, v83, s[6:7]
	v_cndmask_b32_e32 v221, v88, v89, vcc
	v_cndmask_b32_e64 v221, v221, v90, s[4:5]
	v_cndmask_b32_e64 v221, v221, v91, s[6:7]
	s_nop 1
	v_mfma_f32_16x16x4_f32 v[84:87], v218, v220, v[36:39]
	v_mfma_f32_16x16x4_f32 v[84:87], v219, v221, v[84:87]
	ds_read_b32 v218, v172 offset:5120
	ds_read_b32 v219, v172 offset:5136
	v_mfma_f32_16x16x4_f32 v[224:227], v182, v220, v[224:227]
	v_mfma_f32_16x16x4_f32 v[224:227], v186, v221, v[224:227]
	v_mfma_f32_16x16x4_f32 v[228:231], v183, v220, v[228:231]
	v_mfma_f32_16x16x4_f32 v[228:231], v187, v221, v[228:231]
	v_mfma_f32_16x16x4_f32 v[232:235], v184, v220, v[232:235]
	v_mfma_f32_16x16x4_f32 v[232:235], v188, v221, v[232:235]
	v_mfma_f32_16x16x4_f32 v[236:239], v185, v220, v[236:239]
	v_mfma_f32_16x16x4_f32 v[236:239], v189, v221, v[236:239]
	v_add_u32_e32 v173, 0x880, v173
	v_add_u32_e32 v2, 0x880, v2
	v_add_u32_e32 v3, 0x880, v3
	v_add_u32_e32 v5, 0x880, v5
	ds_read2_b32 v[182:183], v173 offset0:0 offset1:16
	ds_read2_b32 v[184:185], v173 offset0:32 offset1:48
	ds_read2_b32 v[186:187], v2 offset0:0 offset1:16
	ds_read2_b32 v[188:189], v2 offset0:32 offset1:48
	ds_read2_b32 v[190:191], v3 offset0:0 offset1:16
	ds_read2_b32 v[192:193], v3 offset0:32 offset1:48
	ds_read2_b32 v[194:195], v5 offset0:0 offset1:16
	ds_read2_b32 v[196:197], v5 offset0:32 offset1:48
	s_mov_b64 exec, s[8:9]
	ds_write_b32 v175, v84 offset:8192
	ds_write_b32 v175, v85 offset:8448
	ds_write_b32 v175, v86 offset:8704
	ds_write_b32 v175, v87 offset:8960
	s_mov_b64 exec, -1
	s_waitcnt lgkmcnt(4)
	v_pk_mul_f32 v[224:225], v[224:225], v[198:199]
	v_pk_mul_f32 v[226:227], v[226:227], v[200:201]
	v_pk_mul_f32 v[228:229], v[228:229], v[202:203]
	v_pk_mul_f32 v[230:231], v[230:231], v[204:205]
	v_mfma_f32_16x16x4_f32 v[36:39], v44, v224, 0
	v_mfma_f32_16x16x4_f32 v[40:43], v45, v225, 0
	v_mfma_f32_16x16x4_f32 v[36:39], v46, v226, v[36:39]
	v_mfma_f32_16x16x4_f32 v[40:43], v47, v227, v[40:43]
	v_pk_mul_f32 v[232:233], v[232:233], v[206:207]
	v_pk_mul_f32 v[234:235], v[234:235], v[208:209]
	v_mfma_f32_16x16x4_f32 v[36:39], v48, v228, v[36:39]
	v_mfma_f32_16x16x4_f32 v[40:43], v49, v229, v[40:43]
	v_mfma_f32_16x16x4_f32 v[36:39], v50, v230, v[36:39]
	v_mfma_f32_16x16x4_f32 v[40:43], v51, v231, v[40:43]
	v_pk_mul_f32 v[236:237], v[236:237], v[210:211]
	v_pk_mul_f32 v[238:239], v[238:239], v[212:213]
	v_mfma_f32_16x16x4_f32 v[36:39], v68, v232, v[36:39]
	v_mfma_f32_16x16x4_f32 v[40:43], v69, v233, v[40:43]
	v_mfma_f32_16x16x4_f32 v[36:39], v70, v234, v[36:39]
	v_mfma_f32_16x16x4_f32 v[40:43], v71, v235, v[40:43]
	v_mfma_f32_16x16x4_f32 v[36:39], v96, v236, v[36:39]
	v_mfma_f32_16x16x4_f32 v[40:43], v97, v237, v[40:43]
	v_mfma_f32_16x16x4_f32 v[36:39], v98, v238, v[36:39]
	v_mfma_f32_16x16x4_f32 v[40:43], v99, v239, v[40:43]
	v_mfma_f32_16x16x4_f32 v[36:39], v216, v214, v[36:39]
	v_mfma_f32_16x16x4_f32 v[40:43], v217, v215, v[40:43]
	s_waitcnt lgkmcnt(0)
	s_barrier
	ds_read_b128 v[44:47], v168 offset:13056
	ds_read_b128 v[48:51], v168 offset:13120
	ds_read_b128 v[68:71], v168 offset:13184
	ds_read_b128 v[96:99], v168 offset:13248
	ds_read_b32 v216, v171 offset:6144
	ds_read_b32 v217, v171 offset:6160
	ds_read_b128 v[198:201], v174 offset:1280
	ds_read_b128 v[202:205], v174 offset:1344
	ds_read_b128 v[206:209], v174 offset:1408
	ds_read_b128 v[210:213], v174 offset:1472
	v_mfma_f32_16x16x4_f32 v[224:227], v190, v214, v[224:227]
	v_mfma_f32_16x16x4_f32 v[224:227], v194, v215, v[224:227]
	v_mfma_f32_16x16x4_f32 v[228:231], v191, v214, v[228:231]
	v_mfma_f32_16x16x4_f32 v[228:231], v195, v215, v[228:231]
	v_mfma_f32_16x16x4_f32 v[232:235], v192, v214, v[232:235]
	v_mfma_f32_16x16x4_f32 v[232:235], v196, v215, v[232:235]
	v_mfma_f32_16x16x4_f32 v[236:239], v193, v214, v[236:239]
	v_mfma_f32_16x16x4_f32 v[236:239], v197, v215, v[236:239]
	ds_read_b32 v214, v169 offset:12288
	ds_read_b32 v215, v169 offset:13312
	v_pk_add_f32 v[80:81], v[36:37], v[40:41]
	v_pk_add_f32 v[82:83], v[38:39], v[42:43]
	v_pk_add_f32 v[84:85], v[36:37], v[40:41]
	v_pk_add_f32 v[86:87], v[38:39], v[42:43]
	v_pk_add_f32 v[36:37], v[36:37], v[40:41]
	v_pk_add_f32 v[38:39], v[38:39], v[42:43]
	v_permlane32_swap_b32_e32 v80, v84
	v_permlane32_swap_b32_e32 v81, v85
	v_permlane32_swap_b32_e32 v82, v86
	v_permlane32_swap_b32_e32 v83, v87
	v_mov_b32_e32 v88, v80
	v_mov_b32_e32 v89, v81
	v_mov_b32_e32 v90, v82
	v_mov_b32_e32 v91, v83
	s_nop 0
	v_permlane16_swap_b32_e32 v80, v88
	v_permlane16_swap_b32_e32 v81, v89
	v_permlane16_swap_b32_e32 v82, v90
	v_permlane16_swap_b32_e32 v83, v91
	v_fmac_f32_e32 v81, v124, v80
	v_fmac_f32_e32 v82, v128, v80
	v_fmac_f32_e32 v83, v132, v80
	v_fmac_f32_e32 v88, v136, v80
	v_fmac_f32_e32 v89, v144, v80
	v_fmac_f32_e32 v90, v152, v80
	v_fmac_f32_e32 v91, v160, v80
	v_fmac_f32_e32 v82, v129, v81
	v_fmac_f32_e32 v83, v133, v81
	v_fmac_f32_e32 v88, v137, v81
	v_fmac_f32_e32 v89, v145, v81
	v_fmac_f32_e32 v90, v153, v81
	v_fmac_f32_e32 v91, v161, v81
	v_fmac_f32_e32 v83, v134, v82
	v_fmac_f32_e32 v88, v138, v82
	v_fmac_f32_e32 v89, v146, v82
	v_fmac_f32_e32 v90, v154, v82
	v_fmac_f32_e32 v91, v162, v82
	v_fmac_f32_e32 v88, v139, v83
	v_fmac_f32_e32 v89, v147, v83
	v_fmac_f32_e32 v90, v155, v83
	v_fmac_f32_e32 v91, v163, v83
	v_fmac_f32_e32 v89, v148, v88
	v_fmac_f32_e32 v90, v156, v88
	v_fmac_f32_e32 v91, v164, v88
	v_fmac_f32_e32 v90, v157, v89
	v_fmac_f32_e32 v91, v165, v89
	v_fmac_f32_e32 v91, v166, v90
	ds_read_b128 v[124:127], v170 offset:6176
	ds_read_b128 v[128:131], v170 offset:6208
	ds_read_b128 v[132:135], v170 offset:6240
	ds_read_b128 v[136:139], v170 offset:6272
	ds_read_b128 v[144:147], v170 offset:6304
	ds_read_b128 v[148:151], v170 offset:6320
	ds_read_b128 v[152:155], v170 offset:6336
	ds_read_b128 v[156:159], v170 offset:6352
	ds_read_b128 v[160:163], v170 offset:6368
	ds_read_b128 v[164:167], v170 offset:6384
	v_cndmask_b32_e32 v220, v80, v81, vcc
	v_cndmask_b32_e64 v220, v220, v82, s[4:5]
	v_cndmask_b32_e64 v220, v220, v83, s[6:7]
	v_cndmask_b32_e32 v221, v88, v89, vcc
	v_cndmask_b32_e64 v221, v221, v90, s[4:5]
	v_cndmask_b32_e64 v221, v221, v91, s[6:7]
	s_nop 1
	v_mfma_f32_16x16x4_f32 v[84:87], v218, v220, v[36:39]
	v_mfma_f32_16x16x4_f32 v[84:87], v219, v221, v[84:87]
	ds_read_b32 v218, v172 offset:6144
	ds_read_b32 v219, v172 offset:6160
	v_mfma_f32_16x16x4_f32 v[224:227], v182, v220, v[224:227]
	v_mfma_f32_16x16x4_f32 v[224:227], v186, v221, v[224:227]
	v_mfma_f32_16x16x4_f32 v[228:231], v183, v220, v[228:231]
	v_mfma_f32_16x16x4_f32 v[228:231], v187, v221, v[228:231]
	v_mfma_f32_16x16x4_f32 v[232:235], v184, v220, v[232:235]
	v_mfma_f32_16x16x4_f32 v[232:235], v188, v221, v[232:235]
	v_mfma_f32_16x16x4_f32 v[236:239], v185, v220, v[236:239]
	v_mfma_f32_16x16x4_f32 v[236:239], v189, v221, v[236:239]
	v_add_u32_e32 v173, 0x880, v173
	v_add_u32_e32 v2, 0x880, v2
	v_add_u32_e32 v3, 0x880, v3
	v_add_u32_e32 v5, 0x880, v5
	ds_read2_b32 v[182:183], v173 offset0:0 offset1:16
	ds_read2_b32 v[184:185], v173 offset0:32 offset1:48
	ds_read2_b32 v[186:187], v2 offset0:0 offset1:16
	ds_read2_b32 v[188:189], v2 offset0:32 offset1:48
	ds_read2_b32 v[190:191], v3 offset0:0 offset1:16
	ds_read2_b32 v[192:193], v3 offset0:32 offset1:48
	ds_read2_b32 v[194:195], v5 offset0:0 offset1:16
	ds_read2_b32 v[196:197], v5 offset0:32 offset1:48
	s_mov_b64 exec, s[8:9]
	ds_write_b32 v175, v84 offset:10240
	ds_write_b32 v175, v85 offset:10496
	ds_write_b32 v175, v86 offset:10752
	ds_write_b32 v175, v87 offset:11008
	s_mov_b64 exec, -1
	s_waitcnt lgkmcnt(4)
	v_pk_mul_f32 v[224:225], v[224:225], v[198:199]
	v_pk_mul_f32 v[226:227], v[226:227], v[200:201]
	v_pk_mul_f32 v[228:229], v[228:229], v[202:203]
	v_pk_mul_f32 v[230:231], v[230:231], v[204:205]
	v_mfma_f32_16x16x4_f32 v[36:39], v44, v224, 0
	v_mfma_f32_16x16x4_f32 v[40:43], v45, v225, 0
	v_mfma_f32_16x16x4_f32 v[36:39], v46, v226, v[36:39]
	v_mfma_f32_16x16x4_f32 v[40:43], v47, v227, v[40:43]
	v_pk_mul_f32 v[232:233], v[232:233], v[206:207]
	v_pk_mul_f32 v[234:235], v[234:235], v[208:209]
	v_mfma_f32_16x16x4_f32 v[36:39], v48, v228, v[36:39]
	v_mfma_f32_16x16x4_f32 v[40:43], v49, v229, v[40:43]
	v_mfma_f32_16x16x4_f32 v[36:39], v50, v230, v[36:39]
	v_mfma_f32_16x16x4_f32 v[40:43], v51, v231, v[40:43]
	v_pk_mul_f32 v[236:237], v[236:237], v[210:211]
	v_pk_mul_f32 v[238:239], v[238:239], v[212:213]
	v_mfma_f32_16x16x4_f32 v[36:39], v68, v232, v[36:39]
	v_mfma_f32_16x16x4_f32 v[40:43], v69, v233, v[40:43]
	v_mfma_f32_16x16x4_f32 v[36:39], v70, v234, v[36:39]
	v_mfma_f32_16x16x4_f32 v[40:43], v71, v235, v[40:43]
	v_mfma_f32_16x16x4_f32 v[36:39], v96, v236, v[36:39]
	v_mfma_f32_16x16x4_f32 v[40:43], v97, v237, v[40:43]
	v_mfma_f32_16x16x4_f32 v[36:39], v98, v238, v[36:39]
	v_mfma_f32_16x16x4_f32 v[40:43], v99, v239, v[40:43]
	v_mfma_f32_16x16x4_f32 v[36:39], v216, v214, v[36:39]
	v_mfma_f32_16x16x4_f32 v[40:43], v217, v215, v[40:43]
	s_waitcnt lgkmcnt(0)
	s_barrier
	ds_read_b128 v[44:47], v168 offset:15232
	ds_read_b128 v[48:51], v168 offset:15296
	ds_read_b128 v[68:71], v168 offset:15360
	ds_read_b128 v[96:99], v168 offset:15424
	ds_read_b32 v216, v171 offset:7168
	ds_read_b32 v217, v171 offset:7184
	ds_read_b128 v[198:201], v174 offset:1536
	ds_read_b128 v[202:205], v174 offset:1600
	ds_read_b128 v[206:209], v174 offset:1664
	ds_read_b128 v[210:213], v174 offset:1728
	v_mfma_f32_16x16x4_f32 v[224:227], v190, v214, v[224:227]
	v_mfma_f32_16x16x4_f32 v[224:227], v194, v215, v[224:227]
	v_mfma_f32_16x16x4_f32 v[228:231], v191, v214, v[228:231]
	v_mfma_f32_16x16x4_f32 v[228:231], v195, v215, v[228:231]
	v_mfma_f32_16x16x4_f32 v[232:235], v192, v214, v[232:235]
	v_mfma_f32_16x16x4_f32 v[232:235], v196, v215, v[232:235]
	v_mfma_f32_16x16x4_f32 v[236:239], v193, v214, v[236:239]
	v_mfma_f32_16x16x4_f32 v[236:239], v197, v215, v[236:239]
	ds_read_b32 v214, v169 offset:14336
	ds_read_b32 v215, v169 offset:15360
	v_pk_add_f32 v[80:81], v[36:37], v[40:41]
	v_pk_add_f32 v[82:83], v[38:39], v[42:43]
	v_pk_add_f32 v[84:85], v[36:37], v[40:41]
	v_pk_add_f32 v[86:87], v[38:39], v[42:43]
	v_pk_add_f32 v[36:37], v[36:37], v[40:41]
	v_pk_add_f32 v[38:39], v[38:39], v[42:43]
	v_permlane32_swap_b32_e32 v80, v84
	v_permlane32_swap_b32_e32 v81, v85
	v_permlane32_swap_b32_e32 v82, v86
	v_permlane32_swap_b32_e32 v83, v87
	v_mov_b32_e32 v88, v80
	v_mov_b32_e32 v89, v81
	v_mov_b32_e32 v90, v82
	v_mov_b32_e32 v91, v83
	s_nop 0
	v_permlane16_swap_b32_e32 v80, v88
	v_permlane16_swap_b32_e32 v81, v89
	v_permlane16_swap_b32_e32 v82, v90
	v_permlane16_swap_b32_e32 v83, v91
	v_fmac_f32_e32 v81, v124, v80
	v_fmac_f32_e32 v82, v128, v80
	v_fmac_f32_e32 v83, v132, v80
	v_fmac_f32_e32 v88, v136, v80
	v_fmac_f32_e32 v89, v144, v80
	v_fmac_f32_e32 v90, v152, v80
	v_fmac_f32_e32 v91, v160, v80
	v_fmac_f32_e32 v82, v129, v81
	v_fmac_f32_e32 v83, v133, v81
	v_fmac_f32_e32 v88, v137, v81
	v_fmac_f32_e32 v89, v145, v81
	v_fmac_f32_e32 v90, v153, v81
	v_fmac_f32_e32 v91, v161, v81
	v_fmac_f32_e32 v83, v134, v82
	v_fmac_f32_e32 v88, v138, v82
	v_fmac_f32_e32 v89, v146, v82
	v_fmac_f32_e32 v90, v154, v82
	v_fmac_f32_e32 v91, v162, v82
	v_fmac_f32_e32 v88, v139, v83
	v_fmac_f32_e32 v89, v147, v83
	v_fmac_f32_e32 v90, v155, v83
	v_fmac_f32_e32 v91, v163, v83
	v_fmac_f32_e32 v89, v148, v88
	v_fmac_f32_e32 v90, v156, v88
	v_fmac_f32_e32 v91, v164, v88
	v_fmac_f32_e32 v90, v157, v89
	v_fmac_f32_e32 v91, v165, v89
	v_fmac_f32_e32 v91, v166, v90
	ds_read_b128 v[124:127], v170 offset:7200
	ds_read_b128 v[128:131], v170 offset:7232
	ds_read_b128 v[132:135], v170 offset:7264
	ds_read_b128 v[136:139], v170 offset:7296
	ds_read_b128 v[144:147], v170 offset:7328
	ds_read_b128 v[148:151], v170 offset:7344
	ds_read_b128 v[152:155], v170 offset:7360
	ds_read_b128 v[156:159], v170 offset:7376
	ds_read_b128 v[160:163], v170 offset:7392
	ds_read_b128 v[164:167], v170 offset:7408
	v_cndmask_b32_e32 v220, v80, v81, vcc
	v_cndmask_b32_e64 v220, v220, v82, s[4:5]
	v_cndmask_b32_e64 v220, v220, v83, s[6:7]
	v_cndmask_b32_e32 v221, v88, v89, vcc
	v_cndmask_b32_e64 v221, v221, v90, s[4:5]
	v_cndmask_b32_e64 v221, v221, v91, s[6:7]
	s_nop 1
	v_mfma_f32_16x16x4_f32 v[84:87], v218, v220, v[36:39]
	v_mfma_f32_16x16x4_f32 v[84:87], v219, v221, v[84:87]
	ds_read_b32 v218, v172 offset:7168
	ds_read_b32 v219, v172 offset:7184
	v_mfma_f32_16x16x4_f32 v[224:227], v182, v220, v[224:227]
	v_mfma_f32_16x16x4_f32 v[224:227], v186, v221, v[224:227]
	v_mfma_f32_16x16x4_f32 v[228:231], v183, v220, v[228:231]
	v_mfma_f32_16x16x4_f32 v[228:231], v187, v221, v[228:231]
	v_mfma_f32_16x16x4_f32 v[232:235], v184, v220, v[232:235]
	v_mfma_f32_16x16x4_f32 v[232:235], v188, v221, v[232:235]
	v_mfma_f32_16x16x4_f32 v[236:239], v185, v220, v[236:239]
	v_mfma_f32_16x16x4_f32 v[236:239], v189, v221, v[236:239]
	v_add_u32_e32 v173, 0x880, v173
	v_add_u32_e32 v2, 0x880, v2
	v_add_u32_e32 v3, 0x880, v3
	v_add_u32_e32 v5, 0x880, v5
	ds_read2_b32 v[182:183], v173 offset0:0 offset1:16
	ds_read2_b32 v[184:185], v173 offset0:32 offset1:48
	ds_read2_b32 v[186:187], v2 offset0:0 offset1:16
	ds_read2_b32 v[188:189], v2 offset0:32 offset1:48
	ds_read2_b32 v[190:191], v3 offset0:0 offset1:16
	ds_read2_b32 v[192:193], v3 offset0:32 offset1:48
	ds_read2_b32 v[194:195], v5 offset0:0 offset1:16
	ds_read2_b32 v[196:197], v5 offset0:32 offset1:48
	s_mov_b64 exec, s[8:9]
	ds_write_b32 v175, v84 offset:12288
	ds_write_b32 v175, v85 offset:12544
	ds_write_b32 v175, v86 offset:12800
	ds_write_b32 v175, v87 offset:13056
	s_mov_b64 exec, -1
	s_waitcnt lgkmcnt(4)
	v_pk_mul_f32 v[224:225], v[224:225], v[198:199]
	v_pk_mul_f32 v[226:227], v[226:227], v[200:201]
	v_pk_mul_f32 v[228:229], v[228:229], v[202:203]
	v_pk_mul_f32 v[230:231], v[230:231], v[204:205]
	v_mfma_f32_16x16x4_f32 v[36:39], v44, v224, 0
	v_mfma_f32_16x16x4_f32 v[40:43], v45, v225, 0
	v_mfma_f32_16x16x4_f32 v[36:39], v46, v226, v[36:39]
	v_mfma_f32_16x16x4_f32 v[40:43], v47, v227, v[40:43]
	v_pk_mul_f32 v[232:233], v[232:233], v[206:207]
	v_pk_mul_f32 v[234:235], v[234:235], v[208:209]
	v_mfma_f32_16x16x4_f32 v[36:39], v48, v228, v[36:39]
	v_mfma_f32_16x16x4_f32 v[40:43], v49, v229, v[40:43]
	v_mfma_f32_16x16x4_f32 v[36:39], v50, v230, v[36:39]
	v_mfma_f32_16x16x4_f32 v[40:43], v51, v231, v[40:43]
	v_pk_mul_f32 v[236:237], v[236:237], v[210:211]
	v_pk_mul_f32 v[238:239], v[238:239], v[212:213]
	v_mfma_f32_16x16x4_f32 v[36:39], v68, v232, v[36:39]
	v_mfma_f32_16x16x4_f32 v[40:43], v69, v233, v[40:43]
	v_mfma_f32_16x16x4_f32 v[36:39], v70, v234, v[36:39]
	v_mfma_f32_16x16x4_f32 v[40:43], v71, v235, v[40:43]
	v_mfma_f32_16x16x4_f32 v[36:39], v96, v236, v[36:39]
	v_mfma_f32_16x16x4_f32 v[40:43], v97, v237, v[40:43]
	v_mfma_f32_16x16x4_f32 v[36:39], v98, v238, v[36:39]
	v_mfma_f32_16x16x4_f32 v[40:43], v99, v239, v[40:43]
	v_mfma_f32_16x16x4_f32 v[36:39], v216, v214, v[36:39]
	v_mfma_f32_16x16x4_f32 v[40:43], v217, v215, v[40:43]
	s_waitcnt lgkmcnt(0)
	s_barrier
	ds_read_b128 v[44:47], v168 offset:17408
	ds_read_b128 v[48:51], v168 offset:17472
	ds_read_b128 v[68:71], v168 offset:17536
	ds_read_b128 v[96:99], v168 offset:17600
	ds_read_b32 v216, v171 offset:8192
	ds_read_b32 v217, v171 offset:8208
	ds_read_b128 v[198:201], v174 offset:1792
	ds_read_b128 v[202:205], v174 offset:1856
	ds_read_b128 v[206:209], v174 offset:1920
	ds_read_b128 v[210:213], v174 offset:1984
	v_mfma_f32_16x16x4_f32 v[224:227], v190, v214, v[224:227]
	v_mfma_f32_16x16x4_f32 v[224:227], v194, v215, v[224:227]
	v_mfma_f32_16x16x4_f32 v[228:231], v191, v214, v[228:231]
	v_mfma_f32_16x16x4_f32 v[228:231], v195, v215, v[228:231]
	v_mfma_f32_16x16x4_f32 v[232:235], v192, v214, v[232:235]
	v_mfma_f32_16x16x4_f32 v[232:235], v196, v215, v[232:235]
	v_mfma_f32_16x16x4_f32 v[236:239], v193, v214, v[236:239]
	v_mfma_f32_16x16x4_f32 v[236:239], v197, v215, v[236:239]
	ds_read_b32 v214, v169 offset:16384
	ds_read_b32 v215, v169 offset:17408
	v_pk_add_f32 v[80:81], v[36:37], v[40:41]
	v_pk_add_f32 v[82:83], v[38:39], v[42:43]
	v_pk_add_f32 v[84:85], v[36:37], v[40:41]
	v_pk_add_f32 v[86:87], v[38:39], v[42:43]
	v_pk_add_f32 v[36:37], v[36:37], v[40:41]
	v_pk_add_f32 v[38:39], v[38:39], v[42:43]
	v_permlane32_swap_b32_e32 v80, v84
	v_permlane32_swap_b32_e32 v81, v85
	v_permlane32_swap_b32_e32 v82, v86
	v_permlane32_swap_b32_e32 v83, v87
	v_mov_b32_e32 v88, v80
	v_mov_b32_e32 v89, v81
	v_mov_b32_e32 v90, v82
	v_mov_b32_e32 v91, v83
	s_nop 0
	v_permlane16_swap_b32_e32 v80, v88
	v_permlane16_swap_b32_e32 v81, v89
	v_permlane16_swap_b32_e32 v82, v90
	v_permlane16_swap_b32_e32 v83, v91
	v_fmac_f32_e32 v81, v124, v80
	v_fmac_f32_e32 v82, v128, v80
	v_fmac_f32_e32 v83, v132, v80
	v_fmac_f32_e32 v88, v136, v80
	v_fmac_f32_e32 v89, v144, v80
	v_fmac_f32_e32 v90, v152, v80
	v_fmac_f32_e32 v91, v160, v80
	v_fmac_f32_e32 v82, v129, v81
	v_fmac_f32_e32 v83, v133, v81
	v_fmac_f32_e32 v88, v137, v81
	v_fmac_f32_e32 v89, v145, v81
	v_fmac_f32_e32 v90, v153, v81
	v_fmac_f32_e32 v91, v161, v81
	v_fmac_f32_e32 v83, v134, v82
	v_fmac_f32_e32 v88, v138, v82
	v_fmac_f32_e32 v89, v146, v82
	v_fmac_f32_e32 v90, v154, v82
	v_fmac_f32_e32 v91, v162, v82
	v_fmac_f32_e32 v88, v139, v83
	v_fmac_f32_e32 v89, v147, v83
	v_fmac_f32_e32 v90, v155, v83
	v_fmac_f32_e32 v91, v163, v83
	v_fmac_f32_e32 v89, v148, v88
	v_fmac_f32_e32 v90, v156, v88
	v_fmac_f32_e32 v91, v164, v88
	v_fmac_f32_e32 v90, v157, v89
	v_fmac_f32_e32 v91, v165, v89
	v_fmac_f32_e32 v91, v166, v90
	ds_read_b128 v[124:127], v170 offset:8224
	ds_read_b128 v[128:131], v170 offset:8256
	ds_read_b128 v[132:135], v170 offset:8288
	ds_read_b128 v[136:139], v170 offset:8320
	ds_read_b128 v[144:147], v170 offset:8352
	ds_read_b128 v[148:151], v170 offset:8368
	ds_read_b128 v[152:155], v170 offset:8384
	ds_read_b128 v[156:159], v170 offset:8400
	ds_read_b128 v[160:163], v170 offset:8416
	ds_read_b128 v[164:167], v170 offset:8432
	v_cndmask_b32_e32 v220, v80, v81, vcc
	v_cndmask_b32_e64 v220, v220, v82, s[4:5]
	v_cndmask_b32_e64 v220, v220, v83, s[6:7]
	v_cndmask_b32_e32 v221, v88, v89, vcc
	v_cndmask_b32_e64 v221, v221, v90, s[4:5]
	v_cndmask_b32_e64 v221, v221, v91, s[6:7]
	s_nop 1
	v_mfma_f32_16x16x4_f32 v[84:87], v218, v220, v[36:39]
	v_mfma_f32_16x16x4_f32 v[84:87], v219, v221, v[84:87]
	ds_read_b32 v218, v172 offset:8192
	ds_read_b32 v219, v172 offset:8208
	v_mfma_f32_16x16x4_f32 v[224:227], v182, v220, v[224:227]
	v_mfma_f32_16x16x4_f32 v[224:227], v186, v221, v[224:227]
	v_mfma_f32_16x16x4_f32 v[228:231], v183, v220, v[228:231]
	v_mfma_f32_16x16x4_f32 v[228:231], v187, v221, v[228:231]
	v_mfma_f32_16x16x4_f32 v[232:235], v184, v220, v[232:235]
	v_mfma_f32_16x16x4_f32 v[232:235], v188, v221, v[232:235]
	v_mfma_f32_16x16x4_f32 v[236:239], v185, v220, v[236:239]
	v_mfma_f32_16x16x4_f32 v[236:239], v189, v221, v[236:239]
	v_add_u32_e32 v173, 0x880, v173
	v_add_u32_e32 v2, 0x880, v2
	v_add_u32_e32 v3, 0x880, v3
	v_add_u32_e32 v5, 0x880, v5
	ds_read2_b32 v[182:183], v173 offset0:0 offset1:16
	ds_read2_b32 v[184:185], v173 offset0:32 offset1:48
	ds_read2_b32 v[186:187], v2 offset0:0 offset1:16
	ds_read2_b32 v[188:189], v2 offset0:32 offset1:48
	ds_read2_b32 v[190:191], v3 offset0:0 offset1:16
	ds_read2_b32 v[192:193], v3 offset0:32 offset1:48
	ds_read2_b32 v[194:195], v5 offset0:0 offset1:16
	ds_read2_b32 v[196:197], v5 offset0:32 offset1:48
	s_mov_b64 exec, s[8:9]
	ds_write_b32 v175, v84 offset:14336
	ds_write_b32 v175, v85 offset:14592
	ds_write_b32 v175, v86 offset:14848
	ds_write_b32 v175, v87 offset:15104
	s_mov_b64 exec, -1
	s_waitcnt lgkmcnt(0)
	s_barrier
	s_nop 7
	v_pk_mul_f32 v[224:225], v[224:225], v[198:199]
	v_pk_mul_f32 v[226:227], v[226:227], v[200:201]
	v_pk_mul_f32 v[228:229], v[228:229], v[202:203]
	v_pk_mul_f32 v[230:231], v[230:231], v[204:205]
	v_pk_mul_f32 v[232:233], v[232:233], v[206:207]
	v_pk_mul_f32 v[234:235], v[234:235], v[208:209]
	v_pk_mul_f32 v[236:237], v[236:237], v[210:211]
	v_pk_mul_f32 v[238:239], v[238:239], v[212:213]
	s_branch .Lrw_done
.Lrw_epi:
	v_and_b32_e32 v166, 63, v180
	v_lshrrev_b32_e32 v167, 6, v180
	v_subrev_u32_e32 v167, 4, v167
	v_add_u32_e32 v124, s72, v166
	v_lshlrev_b32_e32 v156, 2, v124
	v_lshlrev_b32_e32 v124, 1, v124
	v_lshl_add_u32 v124, v167, 10, v124
	s_add_u32 s0, s80, s17
	s_lshl_b32 s0, s0, 10
	s_add_u32 s10, s50, s0
	s_addc_u32 s11, s51, 0
	s_add_u32 s12, s24, s0
	s_addc_u32 s13, s25, 0
	global_load_ushort v128, v124, s[10:11]
	s_add_u32 s10, s10, 0x1000
	s_addc_u32 s11, s11, 0
	global_load_ushort v129, v124, s[10:11]
	s_add_u32 s10, s10, 0x1000
	s_addc_u32 s11, s11, 0
	global_load_ushort v130, v124, s[10:11]
	s_add_u32 s10, s10, 0x1000
	s_addc_u32 s11, s11, 0
	global_load_ushort v131, v124, s[10:11]
	s_add_u32 s10, s10, 0x1000
	s_addc_u32 s11, s11, 0
	global_load_ushort v132, v124, s[10:11]
	s_add_u32 s10, s10, 0x1000
	s_addc_u32 s11, s11, 0
	global_load_ushort v133, v124, s[10:11]
	s_add_u32 s10, s10, 0x1000
	s_addc_u32 s11, s11, 0
	global_load_ushort v134, v124, s[10:11]
	s_add_u32 s10, s10, 0x1000
	s_addc_u32 s11, s11, 0
	global_load_ushort v135, v124, s[10:11]
	s_add_u32 s10, s10, 0x1000
	s_addc_u32 s11, s11, 0
	global_load_ushort v136, v124, s[10:11]
	s_add_u32 s10, s10, 0x1000
	s_addc_u32 s11, s11, 0
	global_load_ushort v137, v124, s[10:11]
	s_add_u32 s10, s10, 0x1000
	s_addc_u32 s11, s11, 0
	global_load_ushort v138, v124, s[10:11]
	s_add_u32 s10, s10, 0x1000
	s_addc_u32 s11, s11, 0
	global_load_ushort v139, v124, s[10:11]
	s_add_u32 s10, s10, 0x1000
	s_addc_u32 s11, s11, 0
	global_load_ushort v140, v124, s[10:11]
	s_add_u32 s10, s10, 0x1000
	s_addc_u32 s11, s11, 0
	global_load_ushort v141, v124, s[10:11]
	s_add_u32 s10, s10, 0x1000
	s_addc_u32 s11, s11, 0
	global_load_ushort v142, v124, s[10:11]
	s_add_u32 s10, s10, 0x1000
	s_addc_u32 s11, s11, 0
	global_load_ushort v143, v124, s[10:11]
	s_add_u32 s10, s10, 0x1000
	s_addc_u32 s11, s11, 0
	global_load_dword v144, v156, s[58:59]
	global_load_dword v145, v156, s[60:61]
	v_lshl_add_u32 v146, v167, 6, v166
	v_lshlrev_b32_e32 v146, 2, v146
	v_add_u32_e32 v147, s41, v146
	v_add_u32_e32 v146, 0x1f800, v146
	v_lshlrev_b32_e32 v148, 2, v167
	v_add_u32_e32 v148, s16, v148
	v_mov_b32_e32 v125, 0xbc800000
	v_mov_b32_e32 v126, 0x3c800000
	v_mov_b32_e32 v127, 0x3a27c5ac
	s_barrier
	s_waitcnt vmcnt(0)
	ds_read_b32 v150, v146 offset:0
	ds_read_b32 v152, v147 offset:0
	ds_read_b32 v154, v148 offset:0
	ds_read_b32 v151, v146 offset:1024
	ds_read_b32 v153, v147 offset:1024
	ds_read_b32 v155, v148 offset:16
	v_lshlrev_b32_e32 v128, 16, v128
	v_lshlrev_b32_e32 v129, 16, v129
	s_waitcnt lgkmcnt(0)
	v_mov_b32_e32 v156, v150
	v_mov_b32_e32 v157, v151
	s_nop 0
	v_add_f32_dpp v156, v156, v156 quad_perm:[1,0,3,2] row_mask:0xf bank_mask:0xf bound_ctrl:1
	v_add_f32_dpp v157, v157, v157 quad_perm:[1,0,3,2] row_mask:0xf bank_mask:0xf bound_ctrl:1
	s_nop 0
	v_add_f32_dpp v156, v156, v156 quad_perm:[2,3,0,1] row_mask:0xf bank_mask:0xf bound_ctrl:1
	v_add_f32_dpp v157, v157, v157 quad_perm:[2,3,0,1] row_mask:0xf bank_mask:0xf bound_ctrl:1
	s_nop 0
	v_add_f32_dpp v156, v156, v156 row_half_mirror row_mask:0xf bank_mask:0xf bound_ctrl:1
	v_add_f32_dpp v157, v157, v157 row_half_mirror row_mask:0xf bank_mask:0xf bound_ctrl:1
	s_nop 0
	v_add_f32_dpp v156, v156, v156 row_mirror row_mask:0xf bank_mask:0xf bound_ctrl:1
	v_add_f32_dpp v157, v157, v157 row_mirror row_mask:0xf bank_mask:0xf bound_ctrl:1
	s_nop 0
	v_add_f32_dpp v156, v156, v156 row_bcast:15 row_mask:0xa bank_mask:0xf
	v_add_f32_dpp v157, v157, v157 row_bcast:15 row_mask:0xa bank_mask:0xf
	s_nop 0
	v_add_f32_dpp v156, v156, v156 row_bcast:31 row_mask:0xc bank_mask:0xf
	v_add_f32_dpp v157, v157, v157 row_bcast:31 row_mask:0xc bank_mask:0xf
	s_nop 0
	v_readlane_b32 s4, v156, 63
	v_readlane_b32 s5, v157, 63
	s_nop 1
	v_fmac_f32_e32 v150, s4, v125
	v_fmac_f32_e32 v151, s5, v125
	v_mul_f32_e32 v158, v150, v150
	v_mul_f32_e32 v159, v151, v151
	v_mul_f32_e32 v162, 0xbfb8aa3b, v128
	v_exp_f32_e32 v162, v162
	v_mul_f32_e32 v163, 0xbfb8aa3b, v129
	v_exp_f32_e32 v163, v163
	v_add_f32_dpp v158, v158, v158 quad_perm:[1,0,3,2] row_mask:0xf bank_mask:0xf bound_ctrl:1
	v_add_f32_dpp v159, v159, v159 quad_perm:[1,0,3,2] row_mask:0xf bank_mask:0xf bound_ctrl:1
	s_nop 0
	v_add_f32_dpp v158, v158, v158 quad_perm:[2,3,0,1] row_mask:0xf bank_mask:0xf bound_ctrl:1
	v_add_f32_dpp v159, v159, v159 quad_perm:[2,3,0,1] row_mask:0xf bank_mask:0xf bound_ctrl:1
	s_nop 0
	v_add_f32_dpp v158, v158, v158 row_half_mirror row_mask:0xf bank_mask:0xf bound_ctrl:1
	v_add_f32_dpp v159, v159, v159 row_half_mirror row_mask:0xf bank_mask:0xf bound_ctrl:1
	s_nop 0
	v_add_f32_dpp v158, v158, v158 row_mirror row_mask:0xf bank_mask:0xf bound_ctrl:1
	v_add_f32_dpp v159, v159, v159 row_mirror row_mask:0xf bank_mask:0xf bound_ctrl:1
	s_nop 0
	v_add_f32_dpp v158, v158, v158 row_bcast:15 row_mask:0xa bank_mask:0xf
	v_add_f32_dpp v159, v159, v159 row_bcast:15 row_mask:0xa bank_mask:0xf
	s_nop 0
	v_add_f32_dpp v158, v158, v158 row_bcast:31 row_mask:0xc bank_mask:0xf
	v_add_f32_dpp v159, v159, v159 row_bcast:31 row_mask:0xc bank_mask:0xf
	s_nop 0
	v_readlane_b32 s6, v158, 63
	v_readlane_b32 s7, v159, 63
	v_add_f32_e32 v162, 1.0, v162
	v_rcp_f32_e32 v162, v162
	v_add_f32_e32 v163, 1.0, v163
	v_rcp_f32_e32 v163, v163
	v_fma_f32 v160, s6, v126, v127
	v_fma_f32 v161, s7, v126, v127
	v_rsq_f32_e32 v160, v160
	v_rsq_f32_e32 v161, v161
	s_nop 0
	v_mul_f32_e32 v164, v150, v160
	v_fma_f32 v164, v144, v164, v145
	v_fmac_f32_e32 v164, v154, v152
	v_mul_f32_e32 v164, v164, v128
	v_mul_f32_e32 v164, v162, v164
	v_mul_f32_e32 v165, v151, v161
	v_fma_f32 v165, v144, v165, v145
	v_fmac_f32_e32 v165, v155, v153
	v_mul_f32_e32 v165, v165, v129
	v_mul_f32_e32 v165, v163, v165
	v_bfe_u32 v156, v164, 16, 1
	v_add3_u32 v164, v164, v156, s97
	v_bfe_u32 v157, v165, 16, 1
	v_add3_u32 v165, v165, v157, s97
	global_store_short_d16_hi v124, v164, s[12:13]
	s_add_u32 s12, s12, 0x1000
	s_addc_u32 s13, s13, 0
	global_store_short_d16_hi v124, v165, s[12:13]
	s_add_u32 s12, s12, 0x1000
	s_addc_u32 s13, s13, 0
	s_barrier
	ds_read_b32 v150, v146 offset:2048
	ds_read_b32 v152, v147 offset:2048
	ds_read_b32 v154, v148 offset:32
	ds_read_b32 v151, v146 offset:3072
	ds_read_b32 v153, v147 offset:3072
	ds_read_b32 v155, v148 offset:48
	v_lshlrev_b32_e32 v130, 16, v130
	v_lshlrev_b32_e32 v131, 16, v131
	s_waitcnt lgkmcnt(0)
	v_mov_b32_e32 v156, v150
	v_mov_b32_e32 v157, v151
	s_nop 0
	v_add_f32_dpp v156, v156, v156 quad_perm:[1,0,3,2] row_mask:0xf bank_mask:0xf bound_ctrl:1
	v_add_f32_dpp v157, v157, v157 quad_perm:[1,0,3,2] row_mask:0xf bank_mask:0xf bound_ctrl:1
	s_nop 0
	v_add_f32_dpp v156, v156, v156 quad_perm:[2,3,0,1] row_mask:0xf bank_mask:0xf bound_ctrl:1
	v_add_f32_dpp v157, v157, v157 quad_perm:[2,3,0,1] row_mask:0xf bank_mask:0xf bound_ctrl:1
	s_nop 0
	v_add_f32_dpp v156, v156, v156 row_half_mirror row_mask:0xf bank_mask:0xf bound_ctrl:1
	v_add_f32_dpp v157, v157, v157 row_half_mirror row_mask:0xf bank_mask:0xf bound_ctrl:1
	s_nop 0
	v_add_f32_dpp v156, v156, v156 row_mirror row_mask:0xf bank_mask:0xf bound_ctrl:1
	v_add_f32_dpp v157, v157, v157 row_mirror row_mask:0xf bank_mask:0xf bound_ctrl:1
	s_nop 0
	v_add_f32_dpp v156, v156, v156 row_bcast:15 row_mask:0xa bank_mask:0xf
	v_add_f32_dpp v157, v157, v157 row_bcast:15 row_mask:0xa bank_mask:0xf
	s_nop 0
	v_add_f32_dpp v156, v156, v156 row_bcast:31 row_mask:0xc bank_mask:0xf
	v_add_f32_dpp v157, v157, v157 row_bcast:31 row_mask:0xc bank_mask:0xf
	s_nop 0
	v_readlane_b32 s4, v156, 63
	v_readlane_b32 s5, v157, 63
	s_nop 1
	v_fmac_f32_e32 v150, s4, v125
	v_fmac_f32_e32 v151, s5, v125
	v_mul_f32_e32 v158, v150, v150
	v_mul_f32_e32 v159, v151, v151
	v_mul_f32_e32 v162, 0xbfb8aa3b, v130
	v_exp_f32_e32 v162, v162
	v_mul_f32_e32 v163, 0xbfb8aa3b, v131
	v_exp_f32_e32 v163, v163
	v_add_f32_dpp v158, v158, v158 quad_perm:[1,0,3,2] row_mask:0xf bank_mask:0xf bound_ctrl:1
	v_add_f32_dpp v159, v159, v159 quad_perm:[1,0,3,2] row_mask:0xf bank_mask:0xf bound_ctrl:1
	s_nop 0
	v_add_f32_dpp v158, v158, v158 quad_perm:[2,3,0,1] row_mask:0xf bank_mask:0xf bound_ctrl:1
	v_add_f32_dpp v159, v159, v159 quad_perm:[2,3,0,1] row_mask:0xf bank_mask:0xf bound_ctrl:1
	s_nop 0
	v_add_f32_dpp v158, v158, v158 row_half_mirror row_mask:0xf bank_mask:0xf bound_ctrl:1
	v_add_f32_dpp v159, v159, v159 row_half_mirror row_mask:0xf bank_mask:0xf bound_ctrl:1
	s_nop 0
	v_add_f32_dpp v158, v158, v158 row_mirror row_mask:0xf bank_mask:0xf bound_ctrl:1
	v_add_f32_dpp v159, v159, v159 row_mirror row_mask:0xf bank_mask:0xf bound_ctrl:1
	s_nop 0
	v_add_f32_dpp v158, v158, v158 row_bcast:15 row_mask:0xa bank_mask:0xf
	v_add_f32_dpp v159, v159, v159 row_bcast:15 row_mask:0xa bank_mask:0xf
	s_nop 0
	v_add_f32_dpp v158, v158, v158 row_bcast:31 row_mask:0xc bank_mask:0xf
	v_add_f32_dpp v159, v159, v159 row_bcast:31 row_mask:0xc bank_mask:0xf
	s_nop 0
	v_readlane_b32 s6, v158, 63
	v_readlane_b32 s7, v159, 63
	v_add_f32_e32 v162, 1.0, v162
	v_rcp_f32_e32 v162, v162
	v_add_f32_e32 v163, 1.0, v163
	v_rcp_f32_e32 v163, v163
	v_fma_f32 v160, s6, v126, v127
	v_fma_f32 v161, s7, v126, v127
	v_rsq_f32_e32 v160, v160
	v_rsq_f32_e32 v161, v161
	s_nop 0
	v_mul_f32_e32 v164, v150, v160
	v_fma_f32 v164, v144, v164, v145
	v_fmac_f32_e32 v164, v154, v152
	v_mul_f32_e32 v164, v164, v130
	v_mul_f32_e32 v164, v162, v164
	v_mul_f32_e32 v165, v151, v161
	v_fma_f32 v165, v144, v165, v145
	v_fmac_f32_e32 v165, v155, v153
	v_mul_f32_e32 v165, v165, v131
	v_mul_f32_e32 v165, v163, v165
	v_bfe_u32 v156, v164, 16, 1
	v_add3_u32 v164, v164, v156, s97
	v_bfe_u32 v157, v165, 16, 1
	v_add3_u32 v165, v165, v157, s97
	global_store_short_d16_hi v124, v164, s[12:13]
	s_add_u32 s12, s12, 0x1000
	s_addc_u32 s13, s13, 0
	global_store_short_d16_hi v124, v165, s[12:13]
	s_add_u32 s12, s12, 0x1000
	s_addc_u32 s13, s13, 0
	s_barrier
	ds_read_b32 v150, v146 offset:4096
	ds_read_b32 v152, v147 offset:4096
	ds_read_b32 v154, v148 offset:64
	ds_read_b32 v151, v146 offset:5120
	ds_read_b32 v153, v147 offset:5120
	ds_read_b32 v155, v148 offset:80
	v_lshlrev_b32_e32 v132, 16, v132
	v_lshlrev_b32_e32 v133, 16, v133
	s_waitcnt lgkmcnt(0)
	v_mov_b32_e32 v156, v150
	v_mov_b32_e32 v157, v151
	s_nop 0
	v_add_f32_dpp v156, v156, v156 quad_perm:[1,0,3,2] row_mask:0xf bank_mask:0xf bound_ctrl:1
	v_add_f32_dpp v157, v157, v157 quad_perm:[1,0,3,2] row_mask:0xf bank_mask:0xf bound_ctrl:1
	s_nop 0
	v_add_f32_dpp v156, v156, v156 quad_perm:[2,3,0,1] row_mask:0xf bank_mask:0xf bound_ctrl:1
	v_add_f32_dpp v157, v157, v157 quad_perm:[2,3,0,1] row_mask:0xf bank_mask:0xf bound_ctrl:1
	s_nop 0
	v_add_f32_dpp v156, v156, v156 row_half_mirror row_mask:0xf bank_mask:0xf bound_ctrl:1
	v_add_f32_dpp v157, v157, v157 row_half_mirror row_mask:0xf bank_mask:0xf bound_ctrl:1
	s_nop 0
	v_add_f32_dpp v156, v156, v156 row_mirror row_mask:0xf bank_mask:0xf bound_ctrl:1
	v_add_f32_dpp v157, v157, v157 row_mirror row_mask:0xf bank_mask:0xf bound_ctrl:1
	s_nop 0
	v_add_f32_dpp v156, v156, v156 row_bcast:15 row_mask:0xa bank_mask:0xf
	v_add_f32_dpp v157, v157, v157 row_bcast:15 row_mask:0xa bank_mask:0xf
	s_nop 0
	v_add_f32_dpp v156, v156, v156 row_bcast:31 row_mask:0xc bank_mask:0xf
	v_add_f32_dpp v157, v157, v157 row_bcast:31 row_mask:0xc bank_mask:0xf
	s_nop 0
	v_readlane_b32 s4, v156, 63
	v_readlane_b32 s5, v157, 63
	s_nop 1
	v_fmac_f32_e32 v150, s4, v125
	v_fmac_f32_e32 v151, s5, v125
	v_mul_f32_e32 v158, v150, v150
	v_mul_f32_e32 v159, v151, v151
	v_mul_f32_e32 v162, 0xbfb8aa3b, v132
	v_exp_f32_e32 v162, v162
	v_mul_f32_e32 v163, 0xbfb8aa3b, v133
	v_exp_f32_e32 v163, v163
	v_add_f32_dpp v158, v158, v158 quad_perm:[1,0,3,2] row_mask:0xf bank_mask:0xf bound_ctrl:1
	v_add_f32_dpp v159, v159, v159 quad_perm:[1,0,3,2] row_mask:0xf bank_mask:0xf bound_ctrl:1
	s_nop 0
	v_add_f32_dpp v158, v158, v158 quad_perm:[2,3,0,1] row_mask:0xf bank_mask:0xf bound_ctrl:1
	v_add_f32_dpp v159, v159, v159 quad_perm:[2,3,0,1] row_mask:0xf bank_mask:0xf bound_ctrl:1
	s_nop 0
	v_add_f32_dpp v158, v158, v158 row_half_mirror row_mask:0xf bank_mask:0xf bound_ctrl:1
	v_add_f32_dpp v159, v159, v159 row_half_mirror row_mask:0xf bank_mask:0xf bound_ctrl:1
	s_nop 0
	v_add_f32_dpp v158, v158, v158 row_mirror row_mask:0xf bank_mask:0xf bound_ctrl:1
	v_add_f32_dpp v159, v159, v159 row_mirror row_mask:0xf bank_mask:0xf bound_ctrl:1
	s_nop 0
	v_add_f32_dpp v158, v158, v158 row_bcast:15 row_mask:0xa bank_mask:0xf
	v_add_f32_dpp v159, v159, v159 row_bcast:15 row_mask:0xa bank_mask:0xf
	s_nop 0
	v_add_f32_dpp v158, v158, v158 row_bcast:31 row_mask:0xc bank_mask:0xf
	v_add_f32_dpp v159, v159, v159 row_bcast:31 row_mask:0xc bank_mask:0xf
	s_nop 0
	v_readlane_b32 s6, v158, 63
	v_readlane_b32 s7, v159, 63
	v_add_f32_e32 v162, 1.0, v162
	v_rcp_f32_e32 v162, v162
	v_add_f32_e32 v163, 1.0, v163
	v_rcp_f32_e32 v163, v163
	v_fma_f32 v160, s6, v126, v127
	v_fma_f32 v161, s7, v126, v127
	v_rsq_f32_e32 v160, v160
	v_rsq_f32_e32 v161, v161
	s_nop 0
	v_mul_f32_e32 v164, v150, v160
	v_fma_f32 v164, v144, v164, v145
	v_fmac_f32_e32 v164, v154, v152
	v_mul_f32_e32 v164, v164, v132
	v_mul_f32_e32 v164, v162, v164
	v_mul_f32_e32 v165, v151, v161
	v_fma_f32 v165, v144, v165, v145
	v_fmac_f32_e32 v165, v155, v153
	v_mul_f32_e32 v165, v165, v133
	v_mul_f32_e32 v165, v163, v165
	v_bfe_u32 v156, v164, 16, 1
	v_add3_u32 v164, v164, v156, s97
	v_bfe_u32 v157, v165, 16, 1
	v_add3_u32 v165, v165, v157, s97
	global_store_short_d16_hi v124, v164, s[12:13]
	s_add_u32 s12, s12, 0x1000
	s_addc_u32 s13, s13, 0
	global_store_short_d16_hi v124, v165, s[12:13]
	s_add_u32 s12, s12, 0x1000
	s_addc_u32 s13, s13, 0
	s_barrier
	ds_read_b32 v150, v146 offset:6144
	ds_read_b32 v152, v147 offset:6144
	ds_read_b32 v154, v148 offset:96
	ds_read_b32 v151, v146 offset:7168
	ds_read_b32 v153, v147 offset:7168
	ds_read_b32 v155, v148 offset:112
	v_lshlrev_b32_e32 v134, 16, v134
	v_lshlrev_b32_e32 v135, 16, v135
	s_waitcnt lgkmcnt(0)
	v_mov_b32_e32 v156, v150
	v_mov_b32_e32 v157, v151
	s_nop 0
	v_add_f32_dpp v156, v156, v156 quad_perm:[1,0,3,2] row_mask:0xf bank_mask:0xf bound_ctrl:1
	v_add_f32_dpp v157, v157, v157 quad_perm:[1,0,3,2] row_mask:0xf bank_mask:0xf bound_ctrl:1
	s_nop 0
	v_add_f32_dpp v156, v156, v156 quad_perm:[2,3,0,1] row_mask:0xf bank_mask:0xf bound_ctrl:1
	v_add_f32_dpp v157, v157, v157 quad_perm:[2,3,0,1] row_mask:0xf bank_mask:0xf bound_ctrl:1
	s_nop 0
	v_add_f32_dpp v156, v156, v156 row_half_mirror row_mask:0xf bank_mask:0xf bound_ctrl:1
	v_add_f32_dpp v157, v157, v157 row_half_mirror row_mask:0xf bank_mask:0xf bound_ctrl:1
	s_nop 0
	v_add_f32_dpp v156, v156, v156 row_mirror row_mask:0xf bank_mask:0xf bound_ctrl:1
	v_add_f32_dpp v157, v157, v157 row_mirror row_mask:0xf bank_mask:0xf bound_ctrl:1
	s_nop 0
	v_add_f32_dpp v156, v156, v156 row_bcast:15 row_mask:0xa bank_mask:0xf
	v_add_f32_dpp v157, v157, v157 row_bcast:15 row_mask:0xa bank_mask:0xf
	s_nop 0
	v_add_f32_dpp v156, v156, v156 row_bcast:31 row_mask:0xc bank_mask:0xf
	v_add_f32_dpp v157, v157, v157 row_bcast:31 row_mask:0xc bank_mask:0xf
	s_nop 0
	v_readlane_b32 s4, v156, 63
	v_readlane_b32 s5, v157, 63
	s_nop 1
	v_fmac_f32_e32 v150, s4, v125
	v_fmac_f32_e32 v151, s5, v125
	v_mul_f32_e32 v158, v150, v150
	v_mul_f32_e32 v159, v151, v151
	v_mul_f32_e32 v162, 0xbfb8aa3b, v134
	v_exp_f32_e32 v162, v162
	v_mul_f32_e32 v163, 0xbfb8aa3b, v135
	v_exp_f32_e32 v163, v163
	v_add_f32_dpp v158, v158, v158 quad_perm:[1,0,3,2] row_mask:0xf bank_mask:0xf bound_ctrl:1
	v_add_f32_dpp v159, v159, v159 quad_perm:[1,0,3,2] row_mask:0xf bank_mask:0xf bound_ctrl:1
	s_nop 0
	v_add_f32_dpp v158, v158, v158 quad_perm:[2,3,0,1] row_mask:0xf bank_mask:0xf bound_ctrl:1
	v_add_f32_dpp v159, v159, v159 quad_perm:[2,3,0,1] row_mask:0xf bank_mask:0xf bound_ctrl:1
	s_nop 0
	v_add_f32_dpp v158, v158, v158 row_half_mirror row_mask:0xf bank_mask:0xf bound_ctrl:1
	v_add_f32_dpp v159, v159, v159 row_half_mirror row_mask:0xf bank_mask:0xf bound_ctrl:1
	s_nop 0
	v_add_f32_dpp v158, v158, v158 row_mirror row_mask:0xf bank_mask:0xf bound_ctrl:1
	v_add_f32_dpp v159, v159, v159 row_mirror row_mask:0xf bank_mask:0xf bound_ctrl:1
	s_nop 0
	v_add_f32_dpp v158, v158, v158 row_bcast:15 row_mask:0xa bank_mask:0xf
	v_add_f32_dpp v159, v159, v159 row_bcast:15 row_mask:0xa bank_mask:0xf
	s_nop 0
	v_add_f32_dpp v158, v158, v158 row_bcast:31 row_mask:0xc bank_mask:0xf
	v_add_f32_dpp v159, v159, v159 row_bcast:31 row_mask:0xc bank_mask:0xf
	s_nop 0
	v_readlane_b32 s6, v158, 63
	v_readlane_b32 s7, v159, 63
	v_add_f32_e32 v162, 1.0, v162
	v_rcp_f32_e32 v162, v162
	v_add_f32_e32 v163, 1.0, v163
	v_rcp_f32_e32 v163, v163
	v_fma_f32 v160, s6, v126, v127
	v_fma_f32 v161, s7, v126, v127
	v_rsq_f32_e32 v160, v160
	v_rsq_f32_e32 v161, v161
	s_nop 0
	v_mul_f32_e32 v164, v150, v160
	v_fma_f32 v164, v144, v164, v145
	v_fmac_f32_e32 v164, v154, v152
	v_mul_f32_e32 v164, v164, v134
	v_mul_f32_e32 v164, v162, v164
	v_mul_f32_e32 v165, v151, v161
	v_fma_f32 v165, v144, v165, v145
	v_fmac_f32_e32 v165, v155, v153
	v_mul_f32_e32 v165, v165, v135
	v_mul_f32_e32 v165, v163, v165
	v_bfe_u32 v156, v164, 16, 1
	v_add3_u32 v164, v164, v156, s97
	v_bfe_u32 v157, v165, 16, 1
	v_add3_u32 v165, v165, v157, s97
	global_store_short_d16_hi v124, v164, s[12:13]
	s_add_u32 s12, s12, 0x1000
	s_addc_u32 s13, s13, 0
	global_store_short_d16_hi v124, v165, s[12:13]
	s_add_u32 s12, s12, 0x1000
	s_addc_u32 s13, s13, 0
	s_barrier
	ds_read_b32 v150, v146 offset:8192
	ds_read_b32 v152, v147 offset:8192
	ds_read_b32 v154, v148 offset:128
	ds_read_b32 v151, v146 offset:9216
	ds_read_b32 v153, v147 offset:9216
	ds_read_b32 v155, v148 offset:144
	v_lshlrev_b32_e32 v136, 16, v136
	v_lshlrev_b32_e32 v137, 16, v137
	s_waitcnt lgkmcnt(0)
	v_mov_b32_e32 v156, v150
	v_mov_b32_e32 v157, v151
	s_nop 0
	v_add_f32_dpp v156, v156, v156 quad_perm:[1,0,3,2] row_mask:0xf bank_mask:0xf bound_ctrl:1
	v_add_f32_dpp v157, v157, v157 quad_perm:[1,0,3,2] row_mask:0xf bank_mask:0xf bound_ctrl:1
	s_nop 0
	v_add_f32_dpp v156, v156, v156 quad_perm:[2,3,0,1] row_mask:0xf bank_mask:0xf bound_ctrl:1
	v_add_f32_dpp v157, v157, v157 quad_perm:[2,3,0,1] row_mask:0xf bank_mask:0xf bound_ctrl:1
	s_nop 0
	v_add_f32_dpp v156, v156, v156 row_half_mirror row_mask:0xf bank_mask:0xf bound_ctrl:1
	v_add_f32_dpp v157, v157, v157 row_half_mirror row_mask:0xf bank_mask:0xf bound_ctrl:1
	s_nop 0
	v_add_f32_dpp v156, v156, v156 row_mirror row_mask:0xf bank_mask:0xf bound_ctrl:1
	v_add_f32_dpp v157, v157, v157 row_mirror row_mask:0xf bank_mask:0xf bound_ctrl:1
	s_nop 0
	v_add_f32_dpp v156, v156, v156 row_bcast:15 row_mask:0xa bank_mask:0xf
	v_add_f32_dpp v157, v157, v157 row_bcast:15 row_mask:0xa bank_mask:0xf
	s_nop 0
	v_add_f32_dpp v156, v156, v156 row_bcast:31 row_mask:0xc bank_mask:0xf
	v_add_f32_dpp v157, v157, v157 row_bcast:31 row_mask:0xc bank_mask:0xf
	s_nop 0
	v_readlane_b32 s4, v156, 63
	v_readlane_b32 s5, v157, 63
	s_nop 1
	v_fmac_f32_e32 v150, s4, v125
	v_fmac_f32_e32 v151, s5, v125
	v_mul_f32_e32 v158, v150, v150
	v_mul_f32_e32 v159, v151, v151
	v_mul_f32_e32 v162, 0xbfb8aa3b, v136
	v_exp_f32_e32 v162, v162
	v_mul_f32_e32 v163, 0xbfb8aa3b, v137
	v_exp_f32_e32 v163, v163
	v_add_f32_dpp v158, v158, v158 quad_perm:[1,0,3,2] row_mask:0xf bank_mask:0xf bound_ctrl:1
	v_add_f32_dpp v159, v159, v159 quad_perm:[1,0,3,2] row_mask:0xf bank_mask:0xf bound_ctrl:1
	s_nop 0
	v_add_f32_dpp v158, v158, v158 quad_perm:[2,3,0,1] row_mask:0xf bank_mask:0xf bound_ctrl:1
	v_add_f32_dpp v159, v159, v159 quad_perm:[2,3,0,1] row_mask:0xf bank_mask:0xf bound_ctrl:1
	s_nop 0
	v_add_f32_dpp v158, v158, v158 row_half_mirror row_mask:0xf bank_mask:0xf bound_ctrl:1
	v_add_f32_dpp v159, v159, v159 row_half_mirror row_mask:0xf bank_mask:0xf bound_ctrl:1
	s_nop 0
	v_add_f32_dpp v158, v158, v158 row_mirror row_mask:0xf bank_mask:0xf bound_ctrl:1
	v_add_f32_dpp v159, v159, v159 row_mirror row_mask:0xf bank_mask:0xf bound_ctrl:1
	s_nop 0
	v_add_f32_dpp v158, v158, v158 row_bcast:15 row_mask:0xa bank_mask:0xf
	v_add_f32_dpp v159, v159, v159 row_bcast:15 row_mask:0xa bank_mask:0xf
	s_nop 0
	v_add_f32_dpp v158, v158, v158 row_bcast:31 row_mask:0xc bank_mask:0xf
	v_add_f32_dpp v159, v159, v159 row_bcast:31 row_mask:0xc bank_mask:0xf
	s_nop 0
	v_readlane_b32 s6, v158, 63
	v_readlane_b32 s7, v159, 63
	v_add_f32_e32 v162, 1.0, v162
	v_rcp_f32_e32 v162, v162
	v_add_f32_e32 v163, 1.0, v163
	v_rcp_f32_e32 v163, v163
	v_fma_f32 v160, s6, v126, v127
	v_fma_f32 v161, s7, v126, v127
	v_rsq_f32_e32 v160, v160
	v_rsq_f32_e32 v161, v161
	s_nop 0
	v_mul_f32_e32 v164, v150, v160
	v_fma_f32 v164, v144, v164, v145
	v_fmac_f32_e32 v164, v154, v152
	v_mul_f32_e32 v164, v164, v136
	v_mul_f32_e32 v164, v162, v164
	v_mul_f32_e32 v165, v151, v161
	v_fma_f32 v165, v144, v165, v145
	v_fmac_f32_e32 v165, v155, v153
	v_mul_f32_e32 v165, v165, v137
	v_mul_f32_e32 v165, v163, v165
	v_bfe_u32 v156, v164, 16, 1
	v_add3_u32 v164, v164, v156, s97
	v_bfe_u32 v157, v165, 16, 1
	v_add3_u32 v165, v165, v157, s97
	global_store_short_d16_hi v124, v164, s[12:13]
	s_add_u32 s12, s12, 0x1000
	s_addc_u32 s13, s13, 0
	global_store_short_d16_hi v124, v165, s[12:13]
	s_add_u32 s12, s12, 0x1000
	s_addc_u32 s13, s13, 0
	s_barrier
	ds_read_b32 v150, v146 offset:10240
	ds_read_b32 v152, v147 offset:10240
	ds_read_b32 v154, v148 offset:160
	ds_read_b32 v151, v146 offset:11264
	ds_read_b32 v153, v147 offset:11264
	ds_read_b32 v155, v148 offset:176
	v_lshlrev_b32_e32 v138, 16, v138
	v_lshlrev_b32_e32 v139, 16, v139
	s_waitcnt lgkmcnt(0)
	v_mov_b32_e32 v156, v150
	v_mov_b32_e32 v157, v151
	s_nop 0
	v_add_f32_dpp v156, v156, v156 quad_perm:[1,0,3,2] row_mask:0xf bank_mask:0xf bound_ctrl:1
	v_add_f32_dpp v157, v157, v157 quad_perm:[1,0,3,2] row_mask:0xf bank_mask:0xf bound_ctrl:1
	s_nop 0
	v_add_f32_dpp v156, v156, v156 quad_perm:[2,3,0,1] row_mask:0xf bank_mask:0xf bound_ctrl:1
	v_add_f32_dpp v157, v157, v157 quad_perm:[2,3,0,1] row_mask:0xf bank_mask:0xf bound_ctrl:1
	s_nop 0
	v_add_f32_dpp v156, v156, v156 row_half_mirror row_mask:0xf bank_mask:0xf bound_ctrl:1
	v_add_f32_dpp v157, v157, v157 row_half_mirror row_mask:0xf bank_mask:0xf bound_ctrl:1
	s_nop 0
	v_add_f32_dpp v156, v156, v156 row_mirror row_mask:0xf bank_mask:0xf bound_ctrl:1
	v_add_f32_dpp v157, v157, v157 row_mirror row_mask:0xf bank_mask:0xf bound_ctrl:1
	s_nop 0
	v_add_f32_dpp v156, v156, v156 row_bcast:15 row_mask:0xa bank_mask:0xf
	v_add_f32_dpp v157, v157, v157 row_bcast:15 row_mask:0xa bank_mask:0xf
	s_nop 0
	v_add_f32_dpp v156, v156, v156 row_bcast:31 row_mask:0xc bank_mask:0xf
	v_add_f32_dpp v157, v157, v157 row_bcast:31 row_mask:0xc bank_mask:0xf
	s_nop 0
	v_readlane_b32 s4, v156, 63
	v_readlane_b32 s5, v157, 63
	s_nop 1
	v_fmac_f32_e32 v150, s4, v125
	v_fmac_f32_e32 v151, s5, v125
	v_mul_f32_e32 v158, v150, v150
	v_mul_f32_e32 v159, v151, v151
	v_mul_f32_e32 v162, 0xbfb8aa3b, v138
	v_exp_f32_e32 v162, v162
	v_mul_f32_e32 v163, 0xbfb8aa3b, v139
	v_exp_f32_e32 v163, v163
	v_add_f32_dpp v158, v158, v158 quad_perm:[1,0,3,2] row_mask:0xf bank_mask:0xf bound_ctrl:1
	v_add_f32_dpp v159, v159, v159 quad_perm:[1,0,3,2] row_mask:0xf bank_mask:0xf bound_ctrl:1
	s_nop 0
	v_add_f32_dpp v158, v158, v158 quad_perm:[2,3,0,1] row_mask:0xf bank_mask:0xf bound_ctrl:1
	v_add_f32_dpp v159, v159, v159 quad_perm:[2,3,0,1] row_mask:0xf bank_mask:0xf bound_ctrl:1
	s_nop 0
	v_add_f32_dpp v158, v158, v158 row_half_mirror row_mask:0xf bank_mask:0xf bound_ctrl:1
	v_add_f32_dpp v159, v159, v159 row_half_mirror row_mask:0xf bank_mask:0xf bound_ctrl:1
	s_nop 0
	v_add_f32_dpp v158, v158, v158 row_mirror row_mask:0xf bank_mask:0xf bound_ctrl:1
	v_add_f32_dpp v159, v159, v159 row_mirror row_mask:0xf bank_mask:0xf bound_ctrl:1
	s_nop 0
	v_add_f32_dpp v158, v158, v158 row_bcast:15 row_mask:0xa bank_mask:0xf
	v_add_f32_dpp v159, v159, v159 row_bcast:15 row_mask:0xa bank_mask:0xf
	s_nop 0
	v_add_f32_dpp v158, v158, v158 row_bcast:31 row_mask:0xc bank_mask:0xf
	v_add_f32_dpp v159, v159, v159 row_bcast:31 row_mask:0xc bank_mask:0xf
	s_nop 0
	v_readlane_b32 s6, v158, 63
	v_readlane_b32 s7, v159, 63
	v_add_f32_e32 v162, 1.0, v162
	v_rcp_f32_e32 v162, v162
	v_add_f32_e32 v163, 1.0, v163
	v_rcp_f32_e32 v163, v163
	v_fma_f32 v160, s6, v126, v127
	v_fma_f32 v161, s7, v126, v127
	v_rsq_f32_e32 v160, v160
	v_rsq_f32_e32 v161, v161
	s_nop 0
	v_mul_f32_e32 v164, v150, v160
	v_fma_f32 v164, v144, v164, v145
	v_fmac_f32_e32 v164, v154, v152
	v_mul_f32_e32 v164, v164, v138
	v_mul_f32_e32 v164, v162, v164
	v_mul_f32_e32 v165, v151, v161
	v_fma_f32 v165, v144, v165, v145
	v_fmac_f32_e32 v165, v155, v153
	v_mul_f32_e32 v165, v165, v139
	v_mul_f32_e32 v165, v163, v165
	v_bfe_u32 v156, v164, 16, 1
	v_add3_u32 v164, v164, v156, s97
	v_bfe_u32 v157, v165, 16, 1
	v_add3_u32 v165, v165, v157, s97
	global_store_short_d16_hi v124, v164, s[12:13]
	s_add_u32 s12, s12, 0x1000
	s_addc_u32 s13, s13, 0
	global_store_short_d16_hi v124, v165, s[12:13]
	s_add_u32 s12, s12, 0x1000
	s_addc_u32 s13, s13, 0
	s_barrier
	ds_read_b32 v150, v146 offset:12288
	ds_read_b32 v152, v147 offset:12288
	ds_read_b32 v154, v148 offset:192
	ds_read_b32 v151, v146 offset:13312
	ds_read_b32 v153, v147 offset:13312
	ds_read_b32 v155, v148 offset:208
	v_lshlrev_b32_e32 v140, 16, v140
	v_lshlrev_b32_e32 v141, 16, v141
	s_waitcnt lgkmcnt(0)
	v_mov_b32_e32 v156, v150
	v_mov_b32_e32 v157, v151
	s_nop 0
	v_add_f32_dpp v156, v156, v156 quad_perm:[1,0,3,2] row_mask:0xf bank_mask:0xf bound_ctrl:1
	v_add_f32_dpp v157, v157, v157 quad_perm:[1,0,3,2] row_mask:0xf bank_mask:0xf bound_ctrl:1
	s_nop 0
	v_add_f32_dpp v156, v156, v156 quad_perm:[2,3,0,1] row_mask:0xf bank_mask:0xf bound_ctrl:1
	v_add_f32_dpp v157, v157, v157 quad_perm:[2,3,0,1] row_mask:0xf bank_mask:0xf bound_ctrl:1
	s_nop 0
	v_add_f32_dpp v156, v156, v156 row_half_mirror row_mask:0xf bank_mask:0xf bound_ctrl:1
	v_add_f32_dpp v157, v157, v157 row_half_mirror row_mask:0xf bank_mask:0xf bound_ctrl:1
	s_nop 0
	v_add_f32_dpp v156, v156, v156 row_mirror row_mask:0xf bank_mask:0xf bound_ctrl:1
	v_add_f32_dpp v157, v157, v157 row_mirror row_mask:0xf bank_mask:0xf bound_ctrl:1
	s_nop 0
	v_add_f32_dpp v156, v156, v156 row_bcast:15 row_mask:0xa bank_mask:0xf
	v_add_f32_dpp v157, v157, v157 row_bcast:15 row_mask:0xa bank_mask:0xf
	s_nop 0
	v_add_f32_dpp v156, v156, v156 row_bcast:31 row_mask:0xc bank_mask:0xf
	v_add_f32_dpp v157, v157, v157 row_bcast:31 row_mask:0xc bank_mask:0xf
	s_nop 0
	v_readlane_b32 s4, v156, 63
	v_readlane_b32 s5, v157, 63
	s_nop 1
	v_fmac_f32_e32 v150, s4, v125
	v_fmac_f32_e32 v151, s5, v125
	v_mul_f32_e32 v158, v150, v150
	v_mul_f32_e32 v159, v151, v151
	v_mul_f32_e32 v162, 0xbfb8aa3b, v140
	v_exp_f32_e32 v162, v162
	v_mul_f32_e32 v163, 0xbfb8aa3b, v141
	v_exp_f32_e32 v163, v163
	v_add_f32_dpp v158, v158, v158 quad_perm:[1,0,3,2] row_mask:0xf bank_mask:0xf bound_ctrl:1
	v_add_f32_dpp v159, v159, v159 quad_perm:[1,0,3,2] row_mask:0xf bank_mask:0xf bound_ctrl:1
	s_nop 0
	v_add_f32_dpp v158, v158, v158 quad_perm:[2,3,0,1] row_mask:0xf bank_mask:0xf bound_ctrl:1
	v_add_f32_dpp v159, v159, v159 quad_perm:[2,3,0,1] row_mask:0xf bank_mask:0xf bound_ctrl:1
	s_nop 0
	v_add_f32_dpp v158, v158, v158 row_half_mirror row_mask:0xf bank_mask:0xf bound_ctrl:1
	v_add_f32_dpp v159, v159, v159 row_half_mirror row_mask:0xf bank_mask:0xf bound_ctrl:1
	s_nop 0
	v_add_f32_dpp v158, v158, v158 row_mirror row_mask:0xf bank_mask:0xf bound_ctrl:1
	v_add_f32_dpp v159, v159, v159 row_mirror row_mask:0xf bank_mask:0xf bound_ctrl:1
	s_nop 0
	v_add_f32_dpp v158, v158, v158 row_bcast:15 row_mask:0xa bank_mask:0xf
	v_add_f32_dpp v159, v159, v159 row_bcast:15 row_mask:0xa bank_mask:0xf
	s_nop 0
	v_add_f32_dpp v158, v158, v158 row_bcast:31 row_mask:0xc bank_mask:0xf
	v_add_f32_dpp v159, v159, v159 row_bcast:31 row_mask:0xc bank_mask:0xf
	s_nop 0
	v_readlane_b32 s6, v158, 63
	v_readlane_b32 s7, v159, 63
	v_add_f32_e32 v162, 1.0, v162
	v_rcp_f32_e32 v162, v162
	v_add_f32_e32 v163, 1.0, v163
	v_rcp_f32_e32 v163, v163
	v_fma_f32 v160, s6, v126, v127
	v_fma_f32 v161, s7, v126, v127
	v_rsq_f32_e32 v160, v160
	v_rsq_f32_e32 v161, v161
	s_nop 0
	v_mul_f32_e32 v164, v150, v160
	v_fma_f32 v164, v144, v164, v145
	v_fmac_f32_e32 v164, v154, v152
	v_mul_f32_e32 v164, v164, v140
	v_mul_f32_e32 v164, v162, v164
	v_mul_f32_e32 v165, v151, v161
	v_fma_f32 v165, v144, v165, v145
	v_fmac_f32_e32 v165, v155, v153
	v_mul_f32_e32 v165, v165, v141
	v_mul_f32_e32 v165, v163, v165
	v_bfe_u32 v156, v164, 16, 1
	v_add3_u32 v164, v164, v156, s97
	v_bfe_u32 v157, v165, 16, 1
	v_add3_u32 v165, v165, v157, s97
	global_store_short_d16_hi v124, v164, s[12:13]
	s_add_u32 s12, s12, 0x1000
	s_addc_u32 s13, s13, 0
	global_store_short_d16_hi v124, v165, s[12:13]
	s_add_u32 s12, s12, 0x1000
	s_addc_u32 s13, s13, 0
	s_barrier
	ds_read_b32 v150, v146 offset:14336
	ds_read_b32 v152, v147 offset:14336
	ds_read_b32 v154, v148 offset:224
	ds_read_b32 v151, v146 offset:15360
	ds_read_b32 v153, v147 offset:15360
	ds_read_b32 v155, v148 offset:240
	v_lshlrev_b32_e32 v142, 16, v142
	v_lshlrev_b32_e32 v143, 16, v143
	s_waitcnt lgkmcnt(0)
	v_mov_b32_e32 v156, v150
	v_mov_b32_e32 v157, v151
	s_nop 0
	v_add_f32_dpp v156, v156, v156 quad_perm:[1,0,3,2] row_mask:0xf bank_mask:0xf bound_ctrl:1
	v_add_f32_dpp v157, v157, v157 quad_perm:[1,0,3,2] row_mask:0xf bank_mask:0xf bound_ctrl:1
	s_nop 0
	v_add_f32_dpp v156, v156, v156 quad_perm:[2,3,0,1] row_mask:0xf bank_mask:0xf bound_ctrl:1
	v_add_f32_dpp v157, v157, v157 quad_perm:[2,3,0,1] row_mask:0xf bank_mask:0xf bound_ctrl:1
	s_nop 0
	v_add_f32_dpp v156, v156, v156 row_half_mirror row_mask:0xf bank_mask:0xf bound_ctrl:1
	v_add_f32_dpp v157, v157, v157 row_half_mirror row_mask:0xf bank_mask:0xf bound_ctrl:1
	s_nop 0
	v_add_f32_dpp v156, v156, v156 row_mirror row_mask:0xf bank_mask:0xf bound_ctrl:1
	v_add_f32_dpp v157, v157, v157 row_mirror row_mask:0xf bank_mask:0xf bound_ctrl:1
	s_nop 0
	v_add_f32_dpp v156, v156, v156 row_bcast:15 row_mask:0xa bank_mask:0xf
	v_add_f32_dpp v157, v157, v157 row_bcast:15 row_mask:0xa bank_mask:0xf
	s_nop 0
	v_add_f32_dpp v156, v156, v156 row_bcast:31 row_mask:0xc bank_mask:0xf
	v_add_f32_dpp v157, v157, v157 row_bcast:31 row_mask:0xc bank_mask:0xf
	s_nop 0
	v_readlane_b32 s4, v156, 63
	v_readlane_b32 s5, v157, 63
	s_nop 1
	v_fmac_f32_e32 v150, s4, v125
	v_fmac_f32_e32 v151, s5, v125
	v_mul_f32_e32 v158, v150, v150
	v_mul_f32_e32 v159, v151, v151
	v_mul_f32_e32 v162, 0xbfb8aa3b, v142
	v_exp_f32_e32 v162, v162
	v_mul_f32_e32 v163, 0xbfb8aa3b, v143
	v_exp_f32_e32 v163, v163
	v_add_f32_dpp v158, v158, v158 quad_perm:[1,0,3,2] row_mask:0xf bank_mask:0xf bound_ctrl:1
	v_add_f32_dpp v159, v159, v159 quad_perm:[1,0,3,2] row_mask:0xf bank_mask:0xf bound_ctrl:1
	s_nop 0
	v_add_f32_dpp v158, v158, v158 quad_perm:[2,3,0,1] row_mask:0xf bank_mask:0xf bound_ctrl:1
	v_add_f32_dpp v159, v159, v159 quad_perm:[2,3,0,1] row_mask:0xf bank_mask:0xf bound_ctrl:1
	s_nop 0
	v_add_f32_dpp v158, v158, v158 row_half_mirror row_mask:0xf bank_mask:0xf bound_ctrl:1
	v_add_f32_dpp v159, v159, v159 row_half_mirror row_mask:0xf bank_mask:0xf bound_ctrl:1
	s_nop 0
	v_add_f32_dpp v158, v158, v158 row_mirror row_mask:0xf bank_mask:0xf bound_ctrl:1
	v_add_f32_dpp v159, v159, v159 row_mirror row_mask:0xf bank_mask:0xf bound_ctrl:1
	s_nop 0
	v_add_f32_dpp v158, v158, v158 row_bcast:15 row_mask:0xa bank_mask:0xf
	v_add_f32_dpp v159, v159, v159 row_bcast:15 row_mask:0xa bank_mask:0xf
	s_nop 0
	v_add_f32_dpp v158, v158, v158 row_bcast:31 row_mask:0xc bank_mask:0xf
	v_add_f32_dpp v159, v159, v159 row_bcast:31 row_mask:0xc bank_mask:0xf
	s_nop 0
	v_readlane_b32 s6, v158, 63
	v_readlane_b32 s7, v159, 63
	v_add_f32_e32 v162, 1.0, v162
	v_rcp_f32_e32 v162, v162
	v_add_f32_e32 v163, 1.0, v163
	v_rcp_f32_e32 v163, v163
	v_fma_f32 v160, s6, v126, v127
	v_fma_f32 v161, s7, v126, v127
	v_rsq_f32_e32 v160, v160
	v_rsq_f32_e32 v161, v161
	s_nop 0
	v_mul_f32_e32 v164, v150, v160
	v_fma_f32 v164, v144, v164, v145
	v_fmac_f32_e32 v164, v154, v152
	v_mul_f32_e32 v164, v164, v142
	v_mul_f32_e32 v164, v162, v164
	v_mul_f32_e32 v165, v151, v161
	v_fma_f32 v165, v144, v165, v145
	v_fmac_f32_e32 v165, v155, v153
	v_mul_f32_e32 v165, v165, v143
	v_mul_f32_e32 v165, v163, v165
	v_bfe_u32 v156, v164, 16, 1
	v_add3_u32 v164, v164, v156, s97
	v_bfe_u32 v157, v165, 16, 1
	v_add3_u32 v165, v165, v157, s97
	global_store_short_d16_hi v124, v164, s[12:13]
	s_add_u32 s12, s12, 0x1000
	s_addc_u32 s13, s13, 0
	global_store_short_d16_hi v124, v165, s[12:13]
	s_add_u32 s12, s12, 0x1000
	s_addc_u32 s13, s13, 0
	s_waitcnt vmcnt(0)

.Lrw_noladder:
	s_add_i32 s40, s40, 1
	s_barrier
	s_cmp_eq_u32 s40, 32
	s_cbranch_scc0 .LBB0_564
	s_branch .LBB0_532
